# v17 with the NSA K-row permutation register moved from v255 to v251 (no functional change)
# baseline (speedup 1.0000x reference)
.LBB0_188:
	v_lshl_add_u64 v[0:1], s[86:87], 0, v[104:105]
	s_mov_b32 s1, 0x15200000
	v_add_co_u32_e32 v0, vcc, s1, v0
	v_cvt_f32_u32_e32 v107, s82
	s_nop 0
	v_addc_co_u32_e32 v1, vcc, 0, v1, vcc
	global_load_dwordx4 v[4:7], v[0:1], off
	s_nop 0
	global_load_dwordx4 v[0:3], v[0:1], off offset:64
	v_cmp_lt_f32_e32 vcc, s72, v107
	s_nop 1
	v_cndmask_b32_e32 v108, 0, v220, vcc
	v_sub_f32_e32 v107, v108, v107
	v_exp_f32_e32 v107, v107
	s_and_b64 vcc, vcc, exec
	s_cselect_b32 s1, 0xffffffc0, 0
	v_ldexp_f32 v152, v107, s1
	global_load_dwordx4 v[108:111], v[16:17], off
	global_load_dwordx4 v[196:199], v[16:17], off offset:64
	global_load_dwordx4 v[112:115], v[16:17], off offset:2048
	global_load_dwordx4 v[200:203], v[16:17], off offset:2112
	global_load_dwordx4 v[116:119], v[26:27], off
	global_load_dwordx4 v[204:207], v[28:29], off
	global_load_dwordx4 v[120:123], v[36:37], off
	global_load_dwordx4 v[228:231], v[38:39], off
	global_load_dwordx4 v[124:127], v[44:45], off
	global_load_dwordx4 v[232:235], v[46:47], off
	global_load_dwordx4 v[128:131], v[52:53], off
	global_load_dwordx4 v[236:239], v[54:55], off
	global_load_dwordx4 v[132:135], v[60:61], off
	global_load_dwordx4 v[136:139], v[68:69], off
	global_load_dwordx4 v[140:143], v[62:63], off
	global_load_dwordx4 v[148:151], v[70:71], off
	s_waitcnt vmcnt(14) lgkmcnt(0)
	v_mfma_f32_16x16x32_bf16 v[108:111], v[108:111], v[4:7], 0
	v_mfma_f32_16x16x32_bf16 v[108:111], v[196:199], v[0:3], v[108:111]
	s_waitcnt vmcnt(12)
	v_mfma_f32_16x16x32_bf16 v[112:115], v[112:115], v[4:7], 0
	v_mfma_f32_16x16x32_bf16 v[112:115], v[200:203], v[0:3], v[112:115]
	s_waitcnt vmcnt(10)
	v_mfma_f32_16x16x32_bf16 v[116:119], v[116:119], v[4:7], 0
	v_mfma_f32_16x16x32_bf16 v[116:119], v[204:207], v[0:3], v[116:119]
	s_waitcnt vmcnt(8)
	v_mfma_f32_16x16x32_bf16 v[120:123], v[120:123], v[4:7], 0
	v_mfma_f32_16x16x32_bf16 v[120:123], v[228:231], v[0:3], v[120:123]
	s_waitcnt vmcnt(6)
	v_mfma_f32_16x16x32_bf16 v[124:127], v[124:127], v[4:7], 0
	v_mfma_f32_16x16x32_bf16 v[124:127], v[232:235], v[0:3], v[124:127]
	s_waitcnt vmcnt(4)
	v_mfma_f32_16x16x32_bf16 v[128:131], v[128:131], v[4:7], 0
	v_mfma_f32_16x16x32_bf16 v[128:131], v[236:239], v[0:3], v[128:131]
	v_pk_mul_f32 v[154:155], v[22:23], v[152:153] op_sel_hi:[1,0]
	v_pk_mul_f32 v[156:157], v[24:25], v[152:153] op_sel_hi:[1,0]
	v_pk_mul_f32 v[180:181], v[40:41], v[152:153] op_sel_hi:[1,0]
	v_pk_mul_f32 v[182:183], v[42:43], v[152:153] op_sel_hi:[1,0]
	v_pk_mul_f32 v[188:189], v[18:19], v[152:153] op_sel_hi:[1,0]
	v_pk_mul_f32 v[158:159], v[72:73], v[152:153] op_sel_hi:[1,0]
	v_pk_mul_f32 v[166:167], v[74:75], v[152:153] op_sel_hi:[1,0]
	v_pk_mul_f32 v[168:169], v[64:65], v[152:153] op_sel_hi:[1,0]
	v_pk_mul_f32 v[170:171], v[66:67], v[152:153] op_sel_hi:[1,0]
	v_pk_mul_f32 v[172:173], v[56:57], v[152:153] op_sel_hi:[1,0]
	v_pk_mul_f32 v[174:175], v[58:59], v[152:153] op_sel_hi:[1,0]
	v_pk_mul_f32 v[176:177], v[48:49], v[152:153] op_sel_hi:[1,0]
	v_pk_mul_f32 v[178:179], v[50:51], v[152:153] op_sel_hi:[1,0]
	v_pk_mul_f32 v[184:185], v[30:31], v[152:153] op_sel_hi:[1,0]
	v_pk_mul_f32 v[186:187], v[34:35], v[152:153] op_sel_hi:[1,0]
	v_pk_mul_f32 v[152:153], v[20:21], v[152:153] op_sel_hi:[1,0]
	v_pk_fma_f32 v[112:113], v[112:113], s[90:91], v[154:155] op_sel_hi:[1,0,1] neg_lo:[0,0,1] neg_hi:[0,0,1]
	v_pk_fma_f32 v[114:115], v[114:115], s[90:91], v[156:157] op_sel_hi:[1,0,1] neg_lo:[0,0,1] neg_hi:[0,0,1]
	v_pk_fma_f32 v[120:121], v[120:121], s[90:91], v[180:181] op_sel_hi:[1,0,1] neg_lo:[0,0,1] neg_hi:[0,0,1]
	v_pk_fma_f32 v[122:123], v[122:123], s[90:91], v[182:183] op_sel_hi:[1,0,1] neg_lo:[0,0,1] neg_hi:[0,0,1]
	v_pk_fma_f32 v[108:109], v[108:109], s[90:91], v[188:189] op_sel_hi:[1,0,1] neg_lo:[0,0,1] neg_hi:[0,0,1]
	v_pk_fma_f32 v[110:111], v[110:111], s[90:91], v[152:153] op_sel_hi:[1,0,1] neg_lo:[0,0,1] neg_hi:[0,0,1]
	v_cndmask_b32_e64 v107, v221, v113, s[14:15]
	v_cndmask_b32_e64 v113, v221, v115, s[16:17]
	v_cndmask_b32_e64 v115, v221, v121, s[34:35]
	v_cndmask_b32_e64 v121, v221, v123, s[36:37]
	v_cndmask_b32_e64 v123, v221, v109, s[6:7]
	v_cndmask_b32_e64 v152, v221, v108, s[4:5]
	v_cndmask_b32_e64 v153, v221, v111, s[8:9]
	v_cndmask_b32_e64 v154, v221, v110, s[10:11]
	v_max3_f32 v108, v152, s73, v123
	v_cndmask_b32_e64 v112, v221, v112, s[12:13]
	v_max3_f32 v108, v108, v154, v153
	v_pk_fma_f32 v[116:117], v[116:117], s[90:91], v[184:185] op_sel_hi:[1,0,1] neg_lo:[0,0,1] neg_hi:[0,0,1]
	v_cndmask_b32_e64 v114, v221, v114, s[20:21]
	v_max3_f32 v155, v108, v112, v107
	v_pk_fma_f32 v[118:119], v[118:119], s[90:91], v[186:187] op_sel_hi:[1,0,1] neg_lo:[0,0,1] neg_hi:[0,0,1]
	v_cndmask_b32_e64 v117, v221, v117, s[24:25]
	v_cndmask_b32_e64 v116, v221, v116, s[22:23]
	v_cndmask_b32_e64 v119, v221, v119, s[26:27]
	v_cndmask_b32_e64 v118, v221, v118, s[28:29]
	v_cndmask_b32_e64 v120, v221, v120, s[30:31]
	v_pk_fma_f32 v[124:125], v[124:125], s[90:91], v[176:177] op_sel_hi:[1,0,1] neg_lo:[0,0,1] neg_hi:[0,0,1]
	v_cndmask_b32_e64 v122, v221, v122, s[38:39]
	v_pk_fma_f32 v[126:127], v[126:127], s[90:91], v[178:179] op_sel_hi:[1,0,1] neg_lo:[0,0,1] neg_hi:[0,0,1]
	v_cndmask_b32_e64 v125, v221, v125, s[44:45]
	v_cndmask_b32_e64 v124, v221, v124, s[42:43]
	v_pk_fma_f32 v[128:129], v[128:129], s[90:91], v[172:173] op_sel_hi:[1,0,1] neg_lo:[0,0,1] neg_hi:[0,0,1]
	v_cndmask_b32_e64 v127, v221, v127, s[40:41]
	v_cndmask_b32_e64 v126, v221, v126, s[46:47]
	v_pk_fma_f32 v[130:131], v[130:131], s[90:91], v[174:175] op_sel_hi:[1,0,1] neg_lo:[0,0,1] neg_hi:[0,0,1]
	v_cndmask_b32_e64 v129, v221, v129, s[52:53]
	v_cndmask_b32_e64 v128, v221, v128, s[50:51]
	v_cndmask_b32_e64 v131, v221, v131, s[48:49]
	v_cndmask_b32_e64 v130, v221, v130, s[54:55]
	v_cmp_lt_f32_e32 vcc, s92, v123
	s_waitcnt vmcnt(0) lgkmcnt(0)
	v_mfma_f32_16x16x32_bf16 v[108:111], v[132:135], v[4:7], 0
	v_max3_f32 v132, v155, v114, v113
	v_max3_f32 v132, v132, v116, v117
	v_max3_f32 v132, v132, v118, v119
	v_mfma_f32_16x16x32_bf16 v[4:7], v[136:139], v[4:7], 0
	v_max3_f32 v132, v132, v120, v115
	v_max3_f32 v132, v132, v122, v121
	v_max3_f32 v132, v132, v124, v125
	v_mfma_f32_16x16x32_bf16 v[108:111], v[140:143], v[0:3], v[108:111]
	v_max3_f32 v132, v132, v126, v127
	v_max3_f32 v132, v132, v128, v129
	v_max3_f32 v132, v132, v130, v131
	v_mfma_f32_16x16x32_bf16 v[0:3], v[148:151], v[0:3], v[4:7]
	s_nop 3
	v_fma_f32 v4, v108, s90, -v168
	v_fma_f32 v5, v109, s90, -v169
	s_nop 1
	v_pk_fma_f32 v[0:1], v[0:1], s[90:91], v[158:159] op_sel_hi:[1,0,1] neg_lo:[0,0,1] neg_hi:[0,0,1]
	v_pk_fma_f32 v[6:7], v[110:111], s[90:91], v[170:171] op_sel_hi:[1,0,1] neg_lo:[0,0,1] neg_hi:[0,0,1]
	v_cndmask_b32_e64 v137, v221, v5, s[60:61]
	v_cndmask_b32_e64 v138, v221, v4, s[58:59]
	v_cndmask_b32_e64 v134, v221, v0, s[66:67]
	v_cndmask_b32_e64 v139, v221, v7, s[56:57]
	v_cndmask_b32_e64 v140, v221, v6, s[62:63]
	v_max3_f32 v0, v132, v138, v137
	v_pk_fma_f32 v[2:3], v[2:3], s[90:91], v[166:167] op_sel_hi:[1,0,1] neg_lo:[0,0,1] neg_hi:[0,0,1]
	v_cndmask_b32_e64 v133, v221, v1, s[68:69]
	v_max3_f32 v0, v0, v140, v139
	v_cndmask_b32_e64 v135, v221, v3, s[64:65]
	v_cndmask_b32_e64 v136, v221, v2, s[70:71]
	v_max3_f32 v0, v0, v134, v133
	v_max3_f32 v0, v0, v136, v135
	ds_bpermute_b32 v1, v193, v0
	s_waitcnt lgkmcnt(0)
	v_max_f32_e32 v1, v1, v1
	v_max_f32_e32 v0, v0, v1
	ds_bpermute_b32 v1, v194, v0
	s_waitcnt lgkmcnt(0)
	v_max_f32_e32 v1, v1, v1
	v_max_f32_e32 v132, v0, v1
	v_sub_f32_e32 v1, v123, v132
	v_sub_f32_e32 v0, v152, v132
	v_mul_f32_e32 v1, 0x3fb8aa3b, v1
	v_sub_f32_e32 v3, v153, v132
	v_mul_f32_e32 v0, 0x3fb8aa3b, v0
	v_exp_f32_e32 v1, v1
	v_sub_f32_e32 v2, v154, v132
	v_mul_f32_e32 v3, 0x3fb8aa3b, v3
	v_exp_f32_e32 v0, v0
	v_sub_f32_e32 v5, v107, v132
	v_mul_f32_e32 v2, 0x3fb8aa3b, v2
	v_exp_f32_e32 v3, v3
	v_sub_f32_e32 v4, v112, v132
	v_mul_f32_e32 v5, 0x3fb8aa3b, v5
	v_exp_f32_e32 v2, v2
	v_mul_f32_e32 v4, 0x3fb8aa3b, v4
	v_exp_f32_e32 v5, v5
	v_cndmask_b32_e32 v1, 0, v1, vcc
	v_cmp_lt_f32_e32 vcc, s92, v152
	v_exp_f32_e32 v4, v4
	v_sub_f32_e32 v7, v113, v132
	v_cndmask_b32_e32 v0, 0, v0, vcc
	v_cmp_lt_f32_e32 vcc, s92, v153
	v_add_f32_e32 v6, 0, v0
	v_add_f32_e32 v6, v1, v6
	v_cndmask_b32_e32 v3, 0, v3, vcc
	v_cmp_lt_f32_e32 vcc, s92, v154
	v_mul_f32_e32 v7, 0x3fb8aa3b, v7
	v_exp_f32_e32 v7, v7
	v_cndmask_b32_e32 v2, 0, v2, vcc
	v_cmp_lt_f32_e32 vcc, s92, v107
	v_add_f32_e32 v6, v2, v6
	v_add_f32_e32 v6, v3, v6
	v_cndmask_b32_e32 v5, 0, v5, vcc
	v_cmp_lt_f32_e32 vcc, s92, v112
	v_sub_f32_e32 v109, v117, v132
	v_sub_f32_e32 v108, v116, v132
	v_cndmask_b32_e32 v4, 0, v4, vcc
	v_add_f32_e32 v6, v4, v6
	v_add_f32_e32 v107, v5, v6
	v_sub_f32_e32 v6, v114, v132
	v_mul_f32_e32 v6, 0x3fb8aa3b, v6
	v_exp_f32_e32 v6, v6
	v_mul_f32_e32 v109, 0x3fb8aa3b, v109
	v_exp_f32_e32 v109, v109
	v_mul_f32_e32 v108, 0x3fb8aa3b, v108
	v_sub_f32_e32 v111, v119, v132
	v_cmp_lt_f32_e32 vcc, s92, v113
	v_exp_f32_e32 v108, v108
	v_sub_f32_e32 v110, v118, v132
	v_mul_f32_e32 v111, 0x3fb8aa3b, v111
	v_cndmask_b32_e32 v7, 0, v7, vcc
	v_cmp_lt_f32_e32 vcc, s92, v114
	v_exp_f32_e32 v111, v111
	v_mul_f32_e32 v110, 0x3fb8aa3b, v110
	v_cndmask_b32_e32 v6, 0, v6, vcc
	v_cmp_lt_f32_e32 vcc, s92, v117
	v_exp_f32_e32 v110, v110
	v_sub_f32_e32 v113, v115, v132
	v_cndmask_b32_e32 v109, 0, v109, vcc
	v_cmp_lt_f32_e32 vcc, s92, v116
	v_sub_f32_e32 v112, v120, v132
	v_mul_f32_e32 v113, 0x3fb8aa3b, v113
	v_cndmask_b32_e32 v108, 0, v108, vcc
	v_cmp_lt_f32_e32 vcc, s92, v119
	v_add_f32_e32 v107, v6, v107
	v_exp_f32_e32 v113, v113
	v_cndmask_b32_e32 v111, 0, v111, vcc
	v_cmp_lt_f32_e32 vcc, s92, v118
	v_mul_f32_e32 v112, 0x3fb8aa3b, v112
	v_add_f32_e32 v107, v7, v107
	v_cndmask_b32_e32 v110, 0, v110, vcc
	v_cmp_lt_f32_e32 vcc, s92, v115
	v_sub_f32_e32 v115, v121, v132
	v_exp_f32_e32 v112, v112
	v_sub_f32_e32 v114, v122, v132
	v_mul_f32_e32 v115, 0x3fb8aa3b, v115
	v_add_f32_e32 v107, v108, v107
	v_exp_f32_e32 v115, v115
	v_mul_f32_e32 v114, 0x3fb8aa3b, v114
	v_sub_f32_e32 v117, v125, v132
	v_add_f32_e32 v107, v109, v107
	v_exp_f32_e32 v114, v114
	v_sub_f32_e32 v116, v124, v132
	v_mul_f32_e32 v117, 0x3fb8aa3b, v117
	v_add_f32_e32 v107, v110, v107
	v_cndmask_b32_e32 v113, 0, v113, vcc
	v_cmp_lt_f32_e32 vcc, s92, v120
	v_exp_f32_e32 v117, v117
	v_mul_f32_e32 v116, 0x3fb8aa3b, v116
	v_sub_f32_e32 v119, v127, v132
	v_add_f32_e32 v107, v111, v107
	v_cndmask_b32_e32 v112, 0, v112, vcc
	v_cmp_lt_f32_e32 vcc, s92, v121
	v_exp_f32_e32 v116, v116
	v_sub_f32_e32 v118, v126, v132
	v_mul_f32_e32 v119, 0x3fb8aa3b, v119
	v_add_f32_e32 v107, v112, v107
	v_cndmask_b32_e32 v115, 0, v115, vcc
	v_cmp_lt_f32_e32 vcc, s92, v122
	v_exp_f32_e32 v119, v119
	v_mul_f32_e32 v118, 0x3fb8aa3b, v118
	v_sub_f32_e32 v121, v129, v132
	v_add_f32_e32 v107, v113, v107
	v_cndmask_b32_e32 v114, 0, v114, vcc
	v_cmp_lt_f32_e32 vcc, s92, v125
	v_exp_f32_e32 v118, v118
	v_sub_f32_e32 v120, v128, v132
	v_mul_f32_e32 v121, 0x3fb8aa3b, v121
	v_add_f32_e32 v107, v114, v107
	v_cndmask_b32_e32 v117, 0, v117, vcc
	v_cmp_lt_f32_e32 vcc, s92, v124
	v_exp_f32_e32 v121, v121
	v_mul_f32_e32 v120, 0x3fb8aa3b, v120
	v_sub_f32_e32 v123, v131, v132
	v_add_f32_e32 v107, v115, v107
	v_cndmask_b32_e32 v116, 0, v116, vcc
	v_cmp_lt_f32_e32 vcc, s92, v127
	v_exp_f32_e32 v120, v120
	v_sub_f32_e32 v122, v130, v132
	v_mul_f32_e32 v123, 0x3fb8aa3b, v123
	v_add_f32_e32 v107, v116, v107
	v_cndmask_b32_e32 v119, 0, v119, vcc
	v_cmp_lt_f32_e32 vcc, s92, v126
	v_exp_f32_e32 v123, v123
	v_mul_f32_e32 v122, 0x3fb8aa3b, v122
	v_sub_f32_e32 v125, v137, v132
	v_add_f32_e32 v107, v117, v107
	v_cndmask_b32_e32 v118, 0, v118, vcc
	v_cmp_lt_f32_e32 vcc, s92, v129
	v_exp_f32_e32 v122, v122
	v_sub_f32_e32 v124, v138, v132
	v_mul_f32_e32 v125, 0x3fb8aa3b, v125
	v_add_f32_e32 v107, v118, v107
	v_cndmask_b32_e32 v121, 0, v121, vcc
	v_cmp_lt_f32_e32 vcc, s92, v128
	v_exp_f32_e32 v125, v125
	v_mul_f32_e32 v124, 0x3fb8aa3b, v124
	v_sub_f32_e32 v127, v139, v132
	v_add_f32_e32 v107, v119, v107
	v_cndmask_b32_e32 v120, 0, v120, vcc
	v_cmp_lt_f32_e32 vcc, s92, v131
	v_exp_f32_e32 v124, v124
	v_sub_f32_e32 v126, v140, v132
	v_mul_f32_e32 v127, 0x3fb8aa3b, v127
	v_add_f32_e32 v107, v120, v107
	v_cndmask_b32_e32 v123, 0, v123, vcc
	v_cmp_lt_f32_e32 vcc, s92, v130
	v_exp_f32_e32 v127, v127
	v_mul_f32_e32 v126, 0x3fb8aa3b, v126
	v_sub_f32_e32 v129, v133, v132
	v_add_f32_e32 v107, v121, v107
	v_cndmask_b32_e32 v122, 0, v122, vcc
	v_cmp_lt_f32_e32 vcc, s92, v137
	v_exp_f32_e32 v126, v126
	v_sub_f32_e32 v128, v134, v132
	v_mul_f32_e32 v129, 0x3fb8aa3b, v129
	v_add_f32_e32 v107, v122, v107
	v_cndmask_b32_e32 v125, 0, v125, vcc
	v_cmp_lt_f32_e32 vcc, s92, v138
	v_exp_f32_e32 v129, v129
	v_mul_f32_e32 v128, 0x3fb8aa3b, v128
	v_sub_f32_e32 v131, v135, v132
	v_add_f32_e32 v107, v123, v107
	v_cndmask_b32_e32 v124, 0, v124, vcc
	v_cmp_lt_f32_e32 vcc, s92, v139
	v_exp_f32_e32 v128, v128
	v_sub_f32_e32 v130, v136, v132
	v_mul_f32_e32 v131, 0x3fb8aa3b, v131
	v_add_f32_e32 v107, v124, v107
	v_cndmask_b32_e32 v127, 0, v127, vcc
	v_cmp_lt_f32_e32 vcc, s92, v140
	v_exp_f32_e32 v131, v131
	v_mul_f32_e32 v130, 0x3fb8aa3b, v130
	v_add_f32_e32 v107, v125, v107
	v_cndmask_b32_e32 v126, 0, v126, vcc
	v_cmp_lt_f32_e32 vcc, s92, v133
	v_exp_f32_e32 v130, v130
	v_add_f32_e32 v107, v126, v107
	v_cndmask_b32_e32 v129, 0, v129, vcc
	v_cmp_lt_f32_e32 vcc, s92, v134
	v_add_f32_e32 v107, v127, v107
	s_nop 0
	v_cndmask_b32_e32 v128, 0, v128, vcc
	v_cmp_lt_f32_e32 vcc, s92, v135
	v_add_f32_e32 v107, v128, v107
	v_add_f32_e32 v107, v129, v107
	v_cndmask_b32_e32 v131, 0, v131, vcc
	v_cmp_lt_f32_e32 vcc, s92, v136
	s_nop 1
	v_cndmask_b32_e32 v130, 0, v130, vcc
	v_add_f32_e32 v107, v130, v107
	v_add_f32_e32 v107, v131, v107
	ds_bpermute_b32 v132, v193, v107
	s_waitcnt lgkmcnt(0)
	v_add_f32_e32 v107, v107, v132
	ds_bpermute_b32 v132, v194, v107
	s_waitcnt lgkmcnt(0)
	v_add_f32_e32 v107, v107, v132
	v_div_scale_f32 v132, vcc, v107, v107, 1.0
	v_rcp_f32_e32 v133, v132
	s_nop 0
	v_fma_f32 v134, -v132, v133, 1.0
	v_fmac_f32_e32 v133, v134, v133
	v_div_scale_f32 v134, vcc, 1.0, v107, 1.0
	v_mul_f32_e32 v135, v134, v133
	v_fma_f32 v136, -v132, v135, v134
	v_fmac_f32_e32 v135, v136, v133
	v_fma_f32 v132, -v132, v135, v134
	v_div_fmas_f32 v132, v132, v133, v135
	v_div_fixup_f32 v132, v132, v107, 1.0
	v_cmp_lt_f32_e32 vcc, 0, v107
	s_nop 1
	v_cndmask_b32_e32 v132, 0, v132, vcc
	v_pk_mul_f32 v[134:135], v[2:3], v[132:133] op_sel_hi:[1,0]
	v_pk_mul_f32 v[136:137], v[6:7], v[132:133] op_sel_hi:[1,0]
	ds_bpermute_b32 v2, v33, v135
	ds_bpermute_b32 v107, v33, v137
	v_pk_mul_f32 v[138:139], v[0:1], v[132:133] op_sel_hi:[1,0]
	v_pk_mul_f32 v[140:141], v[4:5], v[132:133] op_sel_hi:[1,0]
	v_mov_b32_e32 v4, v139
	s_waitcnt lgkmcnt(1)
	v_cndmask_b32_e64 v0, 0, v2, s[18:19]
	s_waitcnt lgkmcnt(0)
	v_cndmask_b32_e64 v1, v2, v107, s[18:19]
	v_mov_b32_e32 v2, v138
	v_mov_b32_e32 v3, v140
	v_mov_b32_e32 v5, v141
	v_pk_add_f32 v[2:3], v[2:3], v[4:5]
	v_mov_b32_e32 v4, v134
	v_mov_b32_e32 v5, v136
	v_mov_b32_e32 v6, v135
	v_mov_b32_e32 v7, v137
	v_pk_add_f32 v[4:5], v[4:5], v[6:7]
	v_pk_mul_f32 v[148:149], v[110:111], v[132:133] op_sel_hi:[1,0]
	v_pk_mul_f32 v[152:153], v[114:115], v[132:133] op_sel_hi:[1,0]
	v_pk_add_f32 v[2:3], v[2:3], v[4:5]
	ds_bpermute_b32 v6, v33, v149
	ds_bpermute_b32 v7, v33, v153
	v_pk_add_f32 v[0:1], v[0:1], v[2:3]
	v_pk_mul_f32 v[142:143], v[108:109], v[132:133] op_sel_hi:[1,0]
	v_pk_mul_f32 v[150:151], v[112:113], v[132:133] op_sel_hi:[1,0]
	v_pk_add_f32 v[14:15], v[14:15], v[0:1]
	v_mov_b32_e32 v0, v142
	v_mov_b32_e32 v1, v150
	v_mov_b32_e32 v2, v143
	v_mov_b32_e32 v3, v151
	v_pk_add_f32 v[0:1], v[0:1], v[2:3]
	v_mov_b32_e32 v2, v148
	v_mov_b32_e32 v3, v152
	v_mov_b32_e32 v4, v149
	v_mov_b32_e32 v5, v153
	v_pk_add_f32 v[2:3], v[2:3], v[4:5]
	v_pk_mul_f32 v[156:157], v[118:119], v[132:133] op_sel_hi:[1,0]
	v_pk_mul_f32 v[166:167], v[122:123], v[132:133] op_sel_hi:[1,0]
	v_pk_add_f32 v[0:1], v[0:1], v[2:3]
	s_waitcnt lgkmcnt(0)
	v_cndmask_b32_e64 v3, v6, v7, s[18:19]
	v_cndmask_b32_e64 v2, v107, v6, s[18:19]
	ds_bpermute_b32 v6, v33, v157
	ds_bpermute_b32 v107, v33, v167
	v_pk_add_f32 v[0:1], v[0:1], v[2:3]
	v_pk_mul_f32 v[154:155], v[116:117], v[132:133] op_sel_hi:[1,0]
	v_pk_mul_f32 v[158:159], v[120:121], v[132:133] op_sel_hi:[1,0]
	v_pk_add_f32 v[12:13], v[12:13], v[0:1]
	v_mov_b32_e32 v0, v154
	v_mov_b32_e32 v1, v158
	v_mov_b32_e32 v2, v155
	v_mov_b32_e32 v3, v159
	v_pk_add_f32 v[0:1], v[0:1], v[2:3]
	v_mov_b32_e32 v2, v156
	v_mov_b32_e32 v3, v166
	v_mov_b32_e32 v4, v157
	v_mov_b32_e32 v5, v167
	v_pk_add_f32 v[2:3], v[2:3], v[4:5]
	v_pk_mul_f32 v[4:5], v[128:129], v[132:133] op_sel_hi:[1,0]
	v_pk_add_f32 v[0:1], v[0:1], v[2:3]
	s_waitcnt lgkmcnt(0)
	v_cndmask_b32_e64 v3, v6, v107, s[18:19]
	v_cndmask_b32_e64 v2, v7, v6, s[18:19]
	v_pk_add_f32 v[0:1], v[0:1], v[2:3]
	v_pk_mul_f32 v[2:3], v[126:127], v[132:133] op_sel_hi:[1,0]
	v_pk_mul_f32 v[6:7], v[130:131], v[132:133] op_sel_hi:[1,0]
	ds_bpermute_b32 v114, v33, v3
	ds_bpermute_b32 v115, v33, v7
	v_pk_add_f32 v[10:11], v[10:11], v[0:1]
	v_pk_mul_f32 v[0:1], v[124:125], v[132:133] op_sel_hi:[1,0]
	v_mov_b32_e32 v109, v4
	v_mov_b32_e32 v108, v0
	v_mov_b32_e32 v110, v1
	v_mov_b32_e32 v111, v5
	v_pk_add_f32 v[108:109], v[108:109], v[110:111]
	v_mov_b32_e32 v110, v2
	v_mov_b32_e32 v111, v6
	v_mov_b32_e32 v112, v3
	v_mov_b32_e32 v113, v7
	v_pk_add_f32 v[110:111], v[110:111], v[112:113]
	s_nop 0
	v_pk_add_f32 v[108:109], v[108:109], v[110:111]
	s_waitcnt lgkmcnt(0)
	v_cndmask_b32_e64 v111, v114, v115, s[18:19]
	v_cndmask_b32_e64 v110, v107, v114, s[18:19]
	v_pk_add_f32 v[108:109], v[108:109], v[110:111]
	s_nop 0
	v_pk_add_f32 v[8:9], v[8:9], v[108:109]
	v_cvt_pk_bf16_f32 v116, v138, v139
	v_cvt_pk_bf16_f32 v117, v134, v135
	v_cvt_pk_bf16_f32 v118, v140, v141
	v_cvt_pk_bf16_f32 v119, v136, v137
	ds_read_b64 v[196:197], v195 offset:0
	ds_read_b64 v[198:199], v195 offset:32
	ds_read_b64 v[200:201], v195 offset:4352
	ds_read_b64 v[202:203], v195 offset:4384
	ds_read_b64 v[204:205], v195 offset:8704
	ds_read_b64 v[206:207], v195 offset:8736
	ds_read_b64 v[228:229], v195 offset:13056
	ds_read_b64 v[230:231], v195 offset:13088
	ds_read_b64 v[232:233], v195 offset:64
	ds_read_b64 v[234:235], v195 offset:96
	ds_read_b64 v[236:237], v195 offset:4416
	ds_read_b64 v[238:239], v195 offset:4448
	ds_read_b64 v[240:241], v195 offset:8768
	ds_read_b64 v[242:243], v195 offset:8800
	ds_read_b64 v[244:245], v195 offset:13120
	ds_read_b64 v[246:247], v195 offset:13152
	global_load_dword v107, v102, s[86:87]
	s_waitcnt lgkmcnt(8)
	s_nop 0
	v_mfma_f32_16x16x32_bf16 v[108:111], v[196:199], v[116:119], 0
	v_mfma_f32_16x16x32_bf16 v[112:115], v[200:203], v[116:119], 0
	v_mfma_f32_16x16x32_bf16 v[120:123], v[204:207], v[116:119], 0
	v_mfma_f32_16x16x32_bf16 v[116:119], v[228:231], v[116:119], 0
	v_cvt_pk_bf16_f32 v124, v142, v143
	v_cvt_pk_bf16_f32 v125, v148, v149
	v_cvt_pk_bf16_f32 v126, v150, v151
	v_cvt_pk_bf16_f32 v127, v152, v153
	ds_read_b64 v[196:197], v195 offset:128
	ds_read_b64 v[198:199], v195 offset:160
	ds_read_b64 v[200:201], v195 offset:4480
	ds_read_b64 v[202:203], v195 offset:4512
	ds_read_b64 v[204:205], v195 offset:8832
	ds_read_b64 v[206:207], v195 offset:8864
	ds_read_b64 v[228:229], v195 offset:13184
	ds_read_b64 v[230:231], v195 offset:13216
	s_waitcnt lgkmcnt(8)
	s_nop 0
	v_mfma_f32_16x16x32_bf16 v[108:111], v[232:235], v[124:127], v[108:111]
	v_mfma_f32_16x16x32_bf16 v[112:115], v[236:239], v[124:127], v[112:115]
	v_mfma_f32_16x16x32_bf16 v[120:123], v[240:243], v[124:127], v[120:123]
	v_mfma_f32_16x16x32_bf16 v[116:119], v[244:247], v[124:127], v[116:119]
	v_cvt_pk_bf16_f32 v124, v154, v155
	v_cvt_pk_bf16_f32 v125, v156, v157
	v_cvt_pk_bf16_f32 v126, v158, v159
	v_cvt_pk_bf16_f32 v127, v166, v167
	ds_read_b64 v[232:233], v195 offset:192
	ds_read_b64 v[234:235], v195 offset:224
	ds_read_b64 v[236:237], v195 offset:4544
	ds_read_b64 v[238:239], v195 offset:4576
	ds_read_b64 v[240:241], v195 offset:8896
	ds_read_b64 v[242:243], v195 offset:8928
	ds_read_b64 v[244:245], v195 offset:13248
	ds_read_b64 v[246:247], v195 offset:13280
	s_waitcnt lgkmcnt(8)
	s_nop 0
	v_mfma_f32_16x16x32_bf16 v[108:111], v[196:199], v[124:127], v[108:111]
	v_mfma_f32_16x16x32_bf16 v[112:115], v[200:203], v[124:127], v[112:115]
	v_mfma_f32_16x16x32_bf16 v[120:123], v[204:207], v[124:127], v[120:123]
	v_mfma_f32_16x16x32_bf16 v[116:119], v[228:231], v[124:127], v[116:119]
	v_cvt_pk_bf16_f32 v0, v0, v1
	v_cvt_pk_bf16_f32 v1, v2, v3
	v_cvt_pk_bf16_f32 v2, v4, v5
	v_cvt_pk_bf16_f32 v3, v6, v7
	s_waitcnt lgkmcnt(0)
	s_nop 0
	v_mfma_f32_16x16x32_bf16 v[4:7], v[232:235], v[0:3], v[108:111]
	s_nop 2
	v_mfma_f32_16x16x32_bf16 v[108:111], v[236:239], v[0:3], v[112:115]
	s_nop 2
	v_mfma_f32_16x16x32_bf16 v[112:115], v[240:243], v[0:3], v[120:123]
	v_mfma_f32_16x16x32_bf16 v[0:3], v[244:247], v[0:3], v[116:119]
	s_nop 2
	v_add_u32_e32 v116, s0, v192
	s_waitcnt vmcnt(0) lgkmcnt(0)
	v_mul_f32_e32 v107, 0xbfb8aa3b, v107
	v_exp_f32_e32 v107, v107
	s_nop 0
	v_add_f32_e32 v107, 1.0, v107
	v_rcp_f32_e32 v107, v107
	s_nop 0
	v_mul_f32_e32 v4, v4, v107
	v_mul_f32_e32 v5, v5, v107
	ds_write2st64_b32 v116, v4, v5 offset1:1
	v_mul_f32_e32 v4, v6, v107
	v_mul_f32_e32 v5, v7, v107
	ds_write2st64_b32 v116, v4, v5 offset0:2 offset1:3
	v_mul_f32_e32 v4, v108, v107
	v_mul_f32_e32 v5, v109, v107
	ds_write2st64_b32 v116, v4, v5 offset0:4 offset1:5
	v_mul_f32_e32 v4, v110, v107
	v_mul_f32_e32 v5, v111, v107
	ds_write2st64_b32 v116, v4, v5 offset0:6 offset1:7
	v_mul_f32_e32 v4, v112, v107
	v_mul_f32_e32 v5, v113, v107
	v_mul_f32_e32 v0, v0, v107
	v_mul_f32_e32 v1, v1, v107
	ds_write2st64_b32 v116, v4, v5 offset0:8 offset1:9
	v_mul_f32_e32 v4, v114, v107
	v_mul_f32_e32 v5, v115, v107
	ds_write2st64_b32 v116, v0, v1 offset0:12 offset1:13
	v_mul_f32_e32 v0, v2, v107
	v_mul_f32_e32 v1, v3, v107
	ds_write2st64_b32 v116, v4, v5 offset0:10 offset1:11
	ds_write2st64_b32 v116, v0, v1 offset0:14 offset1:15
	s_addk_i32 s0, 0x1000
	s_add_i32 s82, s82, 1
	v_lshl_add_u64 v[102:103], v[102:103], 0, 12
	s_cmpk_eq_i32 s0, 0x4000
	v_lshl_add_u64 v[104:105], v[104:105], 0, s[96:97]
	s_cbranch_scc0 .LBB0_188
	s_or_b32 s0, s95, s81
	v_or_b32_e32 v0, s0, v190
	v_ashrrev_i32_e32 v1, 31, v0
	v_lshlrev_b64 v[2:3], 7, v[0:1]
	v_lshl_add_u64 v[2:3], s[86:87], 0, v[2:3]
	s_mul_i32 s82, s2, 48
	v_lshl_add_u64 v[2:3], v[2:3], 0, s[82:83]
	s_mov_b64 s[0:1], 0x2f200020
	v_lshl_add_u64 v[148:149], v[2:3], 0, s[0:1]
	s_lshl_b32 s0, s2, 2
	s_or_b32 s1, s0, 1
	v_cvt_f32_ubyte0_e32 v2, s1
	v_cmp_lt_f32_e32 vcc, s72, v2
	s_or_b32 s1, s0, 2
	v_cvt_f32_ubyte0_e32 v3, s1
	v_cndmask_b32_e32 v6, 0, v220, vcc
	v_sub_f32_e32 v2, v6, v2
	v_exp_f32_e32 v2, v2
	s_or_b32 s1, s0, 3
	s_add_i32 s0, s0, 4
	v_cvt_f32_ubyte0_e32 v4, s1
	v_cvt_f32_ubyte0_e32 v5, s0
	s_and_b64 s[0:1], vcc, exec
	s_cselect_b32 s0, 0xffffffc0, 0
	v_cmp_lt_f32_e32 vcc, s72, v3
	v_ldexp_f32 v34, v2, s0
	s_and_b64 s[0:1], vcc, exec
	v_cndmask_b32_e32 v2, 0, v220, vcc
	v_sub_f32_e32 v2, v2, v3
	v_exp_f32_e32 v2, v2
	s_cselect_b32 s0, 0xffffffc0, 0
	v_cmp_lt_f32_e32 vcc, s72, v4
	v_and_or_b32 v17, v211, 64, v190
	v_ldexp_f32 v35, v2, s0
	v_cndmask_b32_e32 v2, 0, v220, vcc
	v_sub_f32_e32 v2, v2, v4
	v_exp_f32_e32 v2, v2
	s_and_b64 s[0:1], vcc, exec
	s_cselect_b32 s0, 0xffffffc0, 0
	v_cmp_lt_f32_e32 vcc, s72, v5
	v_ldexp_f32 v36, v2, s0
	s_and_b64 s[0:1], vcc, exec
	v_cndmask_b32_e32 v2, 0, v220, vcc
	v_sub_f32_e32 v2, v2, v5
	v_exp_f32_e32 v2, v2
	s_cselect_b32 s0, 0xffffffc0, 0
	s_lshr_b32 s20, s81, 6
	s_add_i32 s22, s20, -1
	v_cmp_eq_u32_e64 s[4:5], s20, v32
	v_cmp_eq_u32_e64 s[6:7], s22, v32
	v_ldexp_f32 v37, v2, s0
	v_cmp_gt_u32_e64 s[0:1], 16, v106
	s_or_b64 s[4:5], s[4:5], s[6:7]
	s_or_b64 s[0:1], s[4:5], s[0:1]
	v_cmp_lt_i32_e32 vcc, s20, v32
	v_cndmask_b32_e64 v2, v14, v222, s[0:1]
	v_lshlrev_b32_e32 v17, 2, v17
	v_cndmask_b32_e32 v14, v2, v221, vcc
	v_add_u32_e32 v2, 4, v32
	v_cmp_eq_u32_e64 s[0:1], 0, v2
	v_cmp_eq_u32_e64 s[6:7], s20, v2
	s_or_b64 s[6:7], s[0:1], s[6:7]
	v_cmp_eq_u32_e64 s[0:1], s22, v2
	s_or_b64 s[0:1], s[6:7], s[0:1]
	v_cmp_lt_i32_e64 s[4:5], s20, v2
	v_cndmask_b32_e64 v3, v15, v222, s[0:1]
	ds_bpermute_b32 v18, v17, v14
	v_cndmask_b32_e64 v15, v3, v221, s[4:5]
	v_add_u32_e32 v3, 8, v32
	v_cmp_eq_u32_e64 s[0:1], 0, v3
	v_cmp_eq_u32_e64 s[8:9], s20, v3
	s_or_b64 s[8:9], s[0:1], s[8:9]
	v_cmp_eq_u32_e64 s[0:1], s22, v3
	s_or_b64 s[0:1], s[8:9], s[0:1]
	v_cmp_lt_i32_e64 s[6:7], s20, v3
	v_cndmask_b32_e64 v4, v12, v222, s[0:1]
	v_cmp_lt_i32_e64 s[24:25], -8, v32
	v_cndmask_b32_e64 v12, v4, v221, s[6:7]
	v_add_u32_e32 v4, 12, v32
	v_cmp_eq_u32_e64 s[0:1], 0, v4
	v_cmp_eq_u32_e64 s[10:11], s20, v4
	s_or_b64 s[10:11], s[0:1], s[10:11]
	v_cmp_eq_u32_e64 s[0:1], s22, v4
	s_or_b64 s[0:1], s[10:11], s[0:1]
	v_cmp_lt_i32_e64 s[8:9], s20, v4
	v_cndmask_b32_e64 v5, v13, v222, s[0:1]
	v_cmp_lt_i32_e64 s[28:29], -12, v32
	v_cndmask_b32_e64 v13, v5, v221, s[8:9]
	v_add_u32_e32 v5, 16, v32
	v_cmp_eq_u32_e64 s[0:1], 0, v5
	v_cmp_eq_u32_e64 s[12:13], s20, v5
	s_or_b64 s[12:13], s[0:1], s[12:13]
	v_cmp_eq_u32_e64 s[0:1], s22, v5
	s_or_b64 s[0:1], s[12:13], s[0:1]
	v_cmp_lt_i32_e64 s[10:11], s20, v5
	v_cndmask_b32_e64 v6, v10, v222, s[0:1]
	v_cmp_lt_i32_e64 s[34:35], -16, v32
	v_cndmask_b32_e64 v10, v6, v221, s[10:11]
	v_add_u32_e32 v6, 20, v32
	v_cmp_eq_u32_e64 s[0:1], 0, v6
	v_cmp_eq_u32_e64 s[14:15], s20, v6
	s_or_b64 s[14:15], s[0:1], s[14:15]
	v_cmp_eq_u32_e64 s[0:1], s22, v6
	s_or_b64 s[0:1], s[14:15], s[0:1]
	v_cmp_lt_i32_e64 s[12:13], s20, v6
	v_cndmask_b32_e64 v7, v11, v222, s[0:1]
	s_movk_i32 s30, 0xffe8
	v_cndmask_b32_e64 v11, v7, v221, s[12:13]
	v_add_u32_e32 v7, 24, v32
	v_cmp_eq_u32_e64 s[0:1], 0, v7
	v_cmp_eq_u32_e64 s[16:17], s20, v7
	s_or_b64 s[16:17], s[0:1], s[16:17]
	v_cmp_eq_u32_e64 s[0:1], s22, v7
	s_or_b64 s[0:1], s[16:17], s[0:1]
	v_cmp_lt_i32_e64 s[14:15], s20, v7
	v_cndmask_b32_e64 v8, v8, v222, s[0:1]
	s_waitcnt lgkmcnt(0)
	v_cmp_eq_f32_e64 s[26:27], v11, v18
	v_cndmask_b32_e64 v16, v8, v221, s[14:15]
	v_add_u32_e32 v8, 28, v32
	v_cmp_lt_i32_e64 s[16:17], s20, v8
	v_cmp_eq_u32_e64 s[0:1], 0, v8
	v_cmp_eq_u32_e64 s[20:21], s20, v8
	s_or_b64 s[20:21], s[0:1], s[20:21]
	v_cmp_eq_u32_e64 s[0:1], s22, v8
	s_or_b64 s[0:1], s[20:21], s[0:1]
	v_cmp_eq_f32_e64 s[20:21], v14, v18
	v_cndmask_b32_e64 v9, v9, v222, s[0:1]
	v_cmp_lt_f32_e64 s[0:1], v14, v18
	s_and_b64 s[20:21], s[18:19], s[20:21]
	s_or_b64 s[0:1], s[0:1], s[20:21]
	v_cmp_eq_f32_e64 s[22:23], v15, v18
	v_cmp_lt_i32_e64 s[20:21], -4, v32
	v_cndmask_b32_e64 v19, 0, 1, s[0:1]
	v_cmp_lt_f32_e64 s[0:1], v15, v18
	s_and_b64 s[22:23], s[20:21], s[22:23]
	s_or_b64 s[0:1], s[0:1], s[22:23]
	v_cmp_eq_f32_e64 s[22:23], v12, v18
	v_cndmask_b32_e64 v20, 0, 1, s[0:1]
	v_cmp_lt_f32_e64 s[0:1], v12, v18
	s_and_b64 s[22:23], s[24:25], s[22:23]
	s_or_b64 s[0:1], s[0:1], s[22:23]
	v_cmp_eq_f32_e64 s[22:23], v13, v18
	v_cndmask_b32_e64 v21, 0, 1, s[0:1]
	v_cmp_lt_f32_e64 s[0:1], v13, v18
	s_and_b64 s[22:23], s[28:29], s[22:23]
	s_or_b64 s[0:1], s[0:1], s[22:23]
	v_cmp_eq_f32_e64 s[22:23], v10, v18
	v_cndmask_b32_e64 v22, 0, 1, s[0:1]
	v_cmp_lt_f32_e64 s[0:1], v10, v18
	s_and_b64 s[22:23], s[34:35], s[22:23]
	s_or_b64 s[0:1], s[0:1], s[22:23]
	v_cndmask_b32_e64 v23, 0, 1, s[0:1]
	s_movk_i32 s0, 0xffec
	v_cmp_lt_i32_e64 s[0:1], s0, v32
	v_cmp_lt_f32_e64 s[22:23], v11, v18
	s_and_b64 s[26:27], s[0:1], s[26:27]
	s_or_b64 s[22:23], s[22:23], s[26:27]
	v_cmp_eq_f32_e64 s[26:27], v16, v18
	v_cmp_lt_i32_e64 s[30:31], s30, v32
	ds_bpermute_b32 v26, v17, v15
	v_cndmask_b32_e64 v9, v9, v221, s[16:17]
	v_cndmask_b32_e64 v24, 0, 1, s[22:23]
	v_cmp_lt_f32_e64 s[22:23], v16, v18
	s_and_b64 s[26:27], s[30:31], s[26:27]
	s_movk_i32 s36, 0xffe4
	s_or_b64 s[22:23], s[22:23], s[26:27]
	v_cmp_eq_f32_e64 s[26:27], v9, v18
	v_cmp_lt_i32_e64 s[36:37], s36, v32
	v_cndmask_b32_e64 v25, 0, 1, s[22:23]
	v_cmp_lt_f32_e64 s[22:23], v9, v18
	s_and_b64 s[26:27], s[36:37], s[26:27]
	s_or_b64 s[22:23], s[22:23], s[26:27]
	v_cndmask_b32_e64 v18, 0, 1, s[22:23]
	s_waitcnt lgkmcnt(0)
	v_cmp_eq_f32_e64 s[36:37], v14, v26
	v_cmp_lt_i32_e64 s[22:23], 4, v32
	v_cmp_lt_f32_e64 s[26:27], v14, v26
	s_and_b64 s[36:37], s[22:23], s[36:37]
	s_or_b64 s[26:27], s[26:27], s[36:37]
	v_addc_co_u32_e64 v19, s[26:27], 0, v19, s[26:27]
	v_cmp_eq_f32_e64 s[36:37], v15, v26
	v_cmp_lt_f32_e64 s[26:27], v15, v26
	s_and_b64 s[36:37], s[18:19], s[36:37]
	s_or_b64 s[26:27], s[26:27], s[36:37]
	v_cmp_eq_f32_e64 s[36:37], v12, v26
	v_cndmask_b32_e64 v27, 0, 1, s[26:27]
	v_cmp_lt_f32_e64 s[26:27], v12, v26
	s_and_b64 s[36:37], s[20:21], s[36:37]
	s_or_b64 s[26:27], s[26:27], s[36:37]
	v_addc_co_u32_e64 v21, s[26:27], 0, v21, s[26:27]
	v_cmp_eq_f32_e64 s[36:37], v13, v26
	v_cmp_lt_f32_e64 s[26:27], v13, v26
	s_and_b64 s[36:37], s[24:25], s[36:37]
	s_or_b64 s[26:27], s[26:27], s[36:37]
	v_cmp_eq_f32_e64 s[36:37], v10, v26
	v_add_u32_e32 v20, v27, v20
	v_cndmask_b32_e64 v27, 0, 1, s[26:27]
	v_cmp_lt_f32_e64 s[26:27], v10, v26
	s_and_b64 s[36:37], s[28:29], s[36:37]
	s_or_b64 s[26:27], s[26:27], s[36:37]
	v_addc_co_u32_e64 v23, s[26:27], 0, v23, s[26:27]
	v_cmp_eq_f32_e64 s[36:37], v11, v26
	v_cmp_lt_f32_e64 s[26:27], v11, v26
	s_and_b64 s[36:37], s[34:35], s[36:37]
	s_or_b64 s[26:27], s[26:27], s[36:37]
	v_cmp_eq_f32_e64 s[36:37], v16, v26
	v_cndmask_b32_e64 v28, 0, 1, s[26:27]
	v_cmp_lt_f32_e64 s[26:27], v16, v26
	s_and_b64 s[36:37], s[0:1], s[36:37]
	ds_bpermute_b32 v29, v17, v12
	s_or_b64 s[26:27], s[26:27], s[36:37]
	v_addc_co_u32_e64 v25, s[26:27], 0, v25, s[26:27]
	v_cmp_eq_f32_e64 s[36:37], v9, v26
	v_cmp_lt_f32_e64 s[26:27], v9, v26
	s_and_b64 s[30:31], s[30:31], s[36:37]
	s_or_b64 s[26:27], s[26:27], s[30:31]
	v_cndmask_b32_e64 v26, 0, 1, s[26:27]
	s_waitcnt lgkmcnt(0)
	v_cmp_eq_f32_e64 s[36:37], v14, v29
	v_cmp_lt_i32_e64 s[26:27], 8, v32
	v_cmp_lt_f32_e64 s[30:31], v14, v29
	s_and_b64 s[36:37], s[26:27], s[36:37]
	s_or_b64 s[30:31], s[30:31], s[36:37]
	v_cmp_eq_f32_e64 s[36:37], v15, v29
	v_cndmask_b32_e64 v30, 0, 1, s[30:31]
	v_cmp_lt_f32_e64 s[30:31], v15, v29
	s_and_b64 s[36:37], s[22:23], s[36:37]
	s_or_b64 s[30:31], s[30:31], s[36:37]
	v_cmp_eq_f32_e64 s[36:37], v12, v29
	v_cndmask_b32_e64 v31, 0, 1, s[30:31]
	v_cmp_lt_f32_e64 s[30:31], v12, v29
	s_and_b64 s[36:37], s[18:19], s[36:37]
	s_or_b64 s[30:31], s[30:31], s[36:37]
	v_cmp_eq_f32_e64 s[36:37], v13, v29
	v_cndmask_b32_e64 v38, 0, 1, s[30:31]
	v_cmp_lt_f32_e64 s[30:31], v13, v29
	s_and_b64 s[36:37], s[20:21], s[36:37]
	s_or_b64 s[30:31], s[30:31], s[36:37]
	v_addc_co_u32_e64 v22, s[30:31], v27, v22, s[30:31]
	v_cmp_eq_f32_e64 s[36:37], v10, v29
	v_cmp_lt_f32_e64 s[30:31], v10, v29
	s_and_b64 s[36:37], s[24:25], s[36:37]
	s_or_b64 s[30:31], s[30:31], s[36:37]
	v_cmp_eq_f32_e64 s[36:37], v11, v29
	v_cndmask_b32_e64 v27, 0, 1, s[30:31]
	v_cmp_lt_f32_e64 s[30:31], v11, v29
	s_and_b64 s[36:37], s[28:29], s[36:37]
	s_or_b64 s[30:31], s[30:31], s[36:37]
	v_addc_co_u32_e64 v24, s[30:31], v28, v24, s[30:31]
	v_cmp_eq_f32_e64 s[36:37], v16, v29
	v_cmp_lt_f32_e64 s[30:31], v16, v29
	s_and_b64 s[36:37], s[34:35], s[36:37]
	s_or_b64 s[30:31], s[30:31], s[36:37]
	v_cmp_eq_f32_e64 s[36:37], v9, v29
	v_cndmask_b32_e64 v28, 0, 1, s[30:31]
	v_cmp_lt_f32_e64 s[30:31], v9, v29
	s_and_b64 s[0:1], s[0:1], s[36:37]
	s_or_b64 s[0:1], s[30:31], s[0:1]
	v_addc_co_u32_e64 v18, s[0:1], v26, v18, s[0:1]
	ds_bpermute_b32 v26, v17, v13
	v_cmp_lt_i32_e64 s[30:31], 12, v32
	v_lshlrev_b32_e64 v2, v2, 1
	v_lshlrev_b32_e64 v3, v3, 1
	v_lshlrev_b32_e64 v4, v4, 1
	s_waitcnt lgkmcnt(0)
	v_cmp_eq_f32_e64 s[36:37], v14, v26
	v_cmp_lt_f32_e64 s[0:1], v14, v26
	s_and_b64 s[36:37], s[30:31], s[36:37]
	s_or_b64 s[0:1], s[0:1], s[36:37]
	v_addc_co_u32_e64 v19, s[0:1], v19, v30, s[0:1]
	v_cmp_eq_f32_e64 s[36:37], v15, v26
	v_cmp_lt_f32_e64 s[0:1], v15, v26
	s_and_b64 s[36:37], s[26:27], s[36:37]
	s_or_b64 s[0:1], s[0:1], s[36:37]
	v_addc_co_u32_e64 v20, s[0:1], v20, v31, s[0:1]
	v_cmp_eq_f32_e64 s[36:37], v12, v26
	v_cmp_lt_f32_e64 s[0:1], v12, v26
	s_and_b64 s[36:37], s[22:23], s[36:37]
	s_or_b64 s[0:1], s[0:1], s[36:37]
	v_addc_co_u32_e64 v21, s[0:1], v21, v38, s[0:1]
	v_cmp_eq_f32_e64 s[36:37], v13, v26
	v_cmp_lt_f32_e64 s[0:1], v13, v26
	s_and_b64 s[36:37], s[18:19], s[36:37]
	s_or_b64 s[0:1], s[0:1], s[36:37]
	v_cmp_eq_f32_e64 s[36:37], v10, v26
	v_cndmask_b32_e64 v29, 0, 1, s[0:1]
	v_cmp_lt_f32_e64 s[0:1], v10, v26
	s_and_b64 s[36:37], s[20:21], s[36:37]
	s_or_b64 s[0:1], s[0:1], s[36:37]
	v_addc_co_u32_e64 v23, s[0:1], v23, v27, s[0:1]
	v_cmp_eq_f32_e64 s[36:37], v11, v26
	v_cmp_lt_f32_e64 s[0:1], v11, v26
	s_and_b64 s[36:37], s[24:25], s[36:37]
	s_or_b64 s[0:1], s[0:1], s[36:37]
	v_cmp_eq_f32_e64 s[36:37], v16, v26
	v_cndmask_b32_e64 v27, 0, 1, s[0:1]
	v_cmp_lt_f32_e64 s[0:1], v16, v26
	s_and_b64 s[36:37], s[28:29], s[36:37]
	s_or_b64 s[0:1], s[0:1], s[36:37]
	v_addc_co_u32_e64 v25, s[0:1], v25, v28, s[0:1]
	ds_bpermute_b32 v28, v17, v10
	v_cmp_eq_f32_e64 s[36:37], v9, v26
	v_cmp_lt_f32_e64 s[0:1], v9, v26
	s_and_b64 s[34:35], s[34:35], s[36:37]
	s_or_b64 s[0:1], s[0:1], s[34:35]
	s_waitcnt lgkmcnt(0)
	v_cmp_eq_f32_e64 s[36:37], v14, v28
	v_cmp_lt_i32_e64 s[34:35], 16, v32
	v_cndmask_b32_e64 v26, 0, 1, s[0:1]
	v_cmp_lt_f32_e64 s[0:1], v14, v28
	s_and_b64 s[36:37], s[34:35], s[36:37]
	s_or_b64 s[0:1], s[0:1], s[36:37]
	v_cmp_eq_f32_e64 s[36:37], v15, v28
	v_add_u32_e32 v22, v22, v29
	v_cndmask_b32_e64 v29, 0, 1, s[0:1]
	v_cmp_lt_f32_e64 s[0:1], v15, v28
	s_and_b64 s[36:37], s[30:31], s[36:37]
	s_or_b64 s[0:1], s[0:1], s[36:37]
	v_cmp_eq_f32_e64 s[36:37], v12, v28
	v_cndmask_b32_e64 v30, 0, 1, s[0:1]
	v_cmp_lt_f32_e64 s[0:1], v12, v28
	s_and_b64 s[36:37], s[26:27], s[36:37]
	s_or_b64 s[0:1], s[0:1], s[36:37]
	v_cmp_eq_f32_e64 s[36:37], v13, v28
	v_cndmask_b32_e64 v31, 0, 1, s[0:1]
	v_cmp_lt_f32_e64 s[0:1], v13, v28
	s_and_b64 s[36:37], s[22:23], s[36:37]
	s_or_b64 s[0:1], s[0:1], s[36:37]
	v_cmp_eq_f32_e64 s[36:37], v10, v28
	v_cndmask_b32_e64 v38, 0, 1, s[0:1]
	v_cmp_lt_f32_e64 s[0:1], v10, v28
	s_and_b64 s[36:37], s[18:19], s[36:37]
	s_or_b64 s[0:1], s[0:1], s[36:37]
	v_cmp_eq_f32_e64 s[36:37], v11, v28
	v_cndmask_b32_e64 v39, 0, 1, s[0:1]
	v_cmp_lt_f32_e64 s[0:1], v11, v28
	s_and_b64 s[36:37], s[20:21], s[36:37]
	s_or_b64 s[0:1], s[0:1], s[36:37]
	v_addc_co_u32_e64 v24, s[0:1], v24, v27, s[0:1]
	v_cmp_eq_f32_e64 s[36:37], v16, v28
	v_cmp_lt_f32_e64 s[0:1], v16, v28
	s_and_b64 s[36:37], s[24:25], s[36:37]
	s_or_b64 s[0:1], s[0:1], s[36:37]
	v_cmp_eq_f32_e64 s[36:37], v9, v28
	v_cndmask_b32_e64 v27, 0, 1, s[0:1]
	v_cmp_lt_f32_e64 s[0:1], v9, v28
	s_and_b64 s[28:29], s[28:29], s[36:37]
	s_or_b64 s[0:1], s[0:1], s[28:29]
	v_addc_co_u32_e64 v18, s[0:1], v18, v26, s[0:1]
	ds_bpermute_b32 v26, v17, v11
	v_cmp_lt_i32_e64 s[0:1], 20, v32
	v_lshlrev_b64 v[0:1], 10, v[0:1]
	s_mov_b32 s38, 1
	v_lshl_add_u64 v[0:1], s[86:87], 0, v[0:1]
	s_waitcnt lgkmcnt(0)
	v_cmp_eq_f32_e64 s[36:37], v14, v26
	v_cmp_lt_f32_e64 s[28:29], v14, v26
	s_and_b64 s[36:37], s[0:1], s[36:37]
	s_or_b64 s[28:29], s[28:29], s[36:37]
	v_addc_co_u32_e64 v19, s[28:29], v19, v29, s[28:29]
	v_cmp_eq_f32_e64 s[36:37], v15, v26
	v_cmp_lt_f32_e64 s[28:29], v15, v26
	s_and_b64 s[36:37], s[34:35], s[36:37]
	s_or_b64 s[28:29], s[28:29], s[36:37]
	v_addc_co_u32_e64 v20, s[28:29], v20, v30, s[28:29]
	v_cmp_eq_f32_e64 s[36:37], v12, v26
	v_cmp_lt_f32_e64 s[28:29], v12, v26
	s_and_b64 s[36:37], s[30:31], s[36:37]
	s_or_b64 s[28:29], s[28:29], s[36:37]
	v_addc_co_u32_e64 v21, s[28:29], v21, v31, s[28:29]
	v_cmp_eq_f32_e64 s[36:37], v13, v26
	v_cmp_lt_f32_e64 s[28:29], v13, v26
	s_and_b64 s[36:37], s[26:27], s[36:37]
	s_or_b64 s[28:29], s[28:29], s[36:37]
	v_addc_co_u32_e64 v22, s[28:29], v22, v38, s[28:29]
	v_cmp_eq_f32_e64 s[36:37], v10, v26
	v_cmp_lt_f32_e64 s[28:29], v10, v26
	s_and_b64 s[36:37], s[22:23], s[36:37]
	s_or_b64 s[28:29], s[28:29], s[36:37]
	v_addc_co_u32_e64 v23, s[28:29], v23, v39, s[28:29]
	v_cmp_eq_f32_e64 s[36:37], v11, v26
	v_cmp_lt_f32_e64 s[28:29], v11, v26
	s_and_b64 s[36:37], s[18:19], s[36:37]
	s_or_b64 s[28:29], s[28:29], s[36:37]
	v_cmp_eq_f32_e64 s[36:37], v16, v26
	v_cndmask_b32_e64 v28, 0, 1, s[28:29]
	v_cmp_lt_f32_e64 s[28:29], v16, v26
	s_and_b64 s[36:37], s[20:21], s[36:37]
	s_or_b64 s[28:29], s[28:29], s[36:37]
	v_addc_co_u32_e64 v25, s[28:29], v25, v27, s[28:29]
	ds_bpermute_b32 v27, v17, v16
	v_cmp_eq_f32_e64 s[36:37], v9, v26
	v_cmp_lt_f32_e64 s[28:29], v9, v26
	s_and_b64 s[24:25], s[24:25], s[36:37]
	s_or_b64 s[24:25], s[28:29], s[24:25]
	s_waitcnt lgkmcnt(0)
	v_cmp_eq_f32_e64 s[28:29], v14, v27
	v_cmp_lt_i32_e64 s[36:37], 24, v32
	v_cndmask_b32_e64 v26, 0, 1, s[24:25]
	v_cmp_lt_f32_e64 s[24:25], v14, v27
	s_and_b64 s[28:29], s[36:37], s[28:29]
	s_or_b64 s[24:25], s[24:25], s[28:29]
	v_cmp_eq_f32_e64 s[28:29], v15, v27
	v_add_u32_e32 v24, v24, v28
	v_cndmask_b32_e64 v28, 0, 1, s[24:25]
	v_cmp_lt_f32_e64 s[24:25], v15, v27
	s_and_b64 s[28:29], s[0:1], s[28:29]
	s_or_b64 s[24:25], s[24:25], s[28:29]
	v_cmp_eq_f32_e64 s[28:29], v12, v27
	v_cndmask_b32_e64 v29, 0, 1, s[24:25]
	v_cmp_lt_f32_e64 s[24:25], v12, v27
	s_and_b64 s[28:29], s[34:35], s[28:29]
	s_or_b64 s[24:25], s[24:25], s[28:29]
	v_cmp_eq_f32_e64 s[28:29], v13, v27
	v_cndmask_b32_e64 v30, 0, 1, s[24:25]
	v_cmp_lt_f32_e64 s[24:25], v13, v27
	s_and_b64 s[28:29], s[30:31], s[28:29]
	s_or_b64 s[24:25], s[24:25], s[28:29]
	v_cmp_eq_f32_e64 s[28:29], v10, v27
	v_cndmask_b32_e64 v31, 0, 1, s[24:25]
	v_cmp_lt_f32_e64 s[24:25], v10, v27
	s_and_b64 s[28:29], s[26:27], s[28:29]
	s_or_b64 s[24:25], s[24:25], s[28:29]
	v_cmp_eq_f32_e64 s[28:29], v11, v27
	v_cndmask_b32_e64 v38, 0, 1, s[24:25]
	v_cmp_lt_f32_e64 s[24:25], v11, v27
	s_and_b64 s[28:29], s[22:23], s[28:29]
	s_or_b64 s[24:25], s[24:25], s[28:29]
	v_cmp_eq_f32_e64 s[28:29], v16, v27
	v_cndmask_b32_e64 v39, 0, 1, s[24:25]
	v_cmp_lt_f32_e64 s[24:25], v16, v27
	s_and_b64 s[28:29], s[18:19], s[28:29]
	s_or_b64 s[24:25], s[24:25], s[28:29]
	v_cmp_eq_f32_e64 s[28:29], v9, v27
	v_cndmask_b32_e64 v40, 0, 1, s[24:25]
	v_cmp_lt_f32_e64 s[24:25], v9, v27
	s_and_b64 s[20:21], s[20:21], s[28:29]
	s_or_b64 s[20:21], s[24:25], s[20:21]
	v_addc_co_u32_e64 v18, s[20:21], v18, v26, s[20:21]
	ds_bpermute_b32 v26, v17, v9
	v_cmp_lt_i32_e64 s[28:29], 28, v32
	v_ashrrev_i32_e32 v33, 31, v32
	s_waitcnt lgkmcnt(0)
	v_cmp_eq_f32_e64 s[24:25], v14, v26
	v_cmp_lt_f32_e64 s[20:21], v14, v26
	s_and_b64 s[24:25], s[28:29], s[24:25]
	s_or_b64 s[20:21], s[20:21], s[24:25]
	v_addc_co_u32_e64 v19, s[20:21], v19, v28, s[20:21]
	v_cmp_eq_f32_e64 s[24:25], v15, v26
	v_cmp_lt_f32_e64 s[20:21], v15, v26
	s_and_b64 s[24:25], s[36:37], s[24:25]
	s_or_b64 s[20:21], s[20:21], s[24:25]
	v_addc_co_u32_e64 v20, s[20:21], v20, v29, s[20:21]
	v_cmp_eq_f32_e64 s[24:25], v12, v26
	v_cmp_lt_f32_e64 s[20:21], v12, v26
	s_and_b64 s[0:1], s[0:1], s[24:25]
	s_or_b64 s[0:1], s[20:21], s[0:1]
	v_addc_co_u32_e64 v21, s[0:1], v21, v30, s[0:1]
	v_cmp_eq_f32_e64 s[20:21], v13, v26
	v_cmp_lt_f32_e64 s[0:1], v13, v26
	s_and_b64 s[20:21], s[34:35], s[20:21]
	s_or_b64 s[0:1], s[0:1], s[20:21]
	v_addc_co_u32_e64 v22, s[0:1], v22, v31, s[0:1]
	v_cmp_eq_f32_e64 s[20:21], v10, v26
	v_cmp_lt_f32_e64 s[0:1], v10, v26
	s_and_b64 s[20:21], s[30:31], s[20:21]
	s_or_b64 s[0:1], s[0:1], s[20:21]
	v_addc_co_u32_e64 v23, s[0:1], v23, v38, s[0:1]
	v_cmp_eq_f32_e64 s[20:21], v11, v26
	v_cmp_lt_f32_e64 s[0:1], v11, v26
	s_and_b64 s[20:21], s[26:27], s[20:21]
	s_or_b64 s[0:1], s[0:1], s[20:21]
	v_addc_co_u32_e64 v24, s[0:1], v24, v39, s[0:1]
	v_cmp_eq_f32_e64 s[20:21], v16, v26
	v_cmp_lt_f32_e64 s[0:1], v16, v26
	s_and_b64 s[20:21], s[22:23], s[20:21]
	s_or_b64 s[0:1], s[0:1], s[20:21]
	v_addc_co_u32_e64 v25, s[0:1], v25, v40, s[0:1]
	v_cmp_eq_f32_e64 s[20:21], v9, v26
	v_cmp_lt_f32_e64 s[0:1], v9, v26
	s_and_b64 s[18:19], s[18:19], s[20:21]
	s_or_b64 s[0:1], s[0:1], s[18:19]
	v_cndmask_b32_e64 v26, 0, 1, s[0:1]
	v_add_u32_e32 v18, v18, v26
	ds_bpermute_b32 v26, v17, v14 offset:64
	v_cmp_lt_i32_e64 s[18:19], 1, v32
	v_cmp_lt_i32_e64 s[24:25], -7, v32
	v_cmp_lt_i32_e64 s[28:29], -11, v32
	v_cmp_lt_i32_e64 s[34:35], -15, v32
	s_waitcnt lgkmcnt(0)
	v_cmp_eq_f32_e64 s[20:21], v14, v26
	v_cmp_lt_f32_e64 s[0:1], v14, v26
	s_and_b64 s[20:21], s[18:19], s[20:21]
	s_or_b64 s[0:1], s[0:1], s[20:21]
	v_cmp_eq_f32_e64 s[22:23], v15, v26
	v_cmp_lt_i32_e64 s[20:21], -3, v32
	v_cndmask_b32_e64 v27, 0, 1, s[0:1]
	v_cmp_lt_f32_e64 s[0:1], v15, v26
	s_and_b64 s[22:23], s[20:21], s[22:23]
	s_or_b64 s[0:1], s[0:1], s[22:23]
	v_cmp_eq_f32_e64 s[22:23], v12, v26
	v_cndmask_b32_e64 v28, 0, 1, s[0:1]
	v_cmp_lt_f32_e64 s[0:1], v12, v26
	s_and_b64 s[22:23], s[24:25], s[22:23]
	s_or_b64 s[0:1], s[0:1], s[22:23]
	v_cmp_eq_f32_e64 s[22:23], v13, v26
	v_cndmask_b32_e64 v29, 0, 1, s[0:1]
	v_cmp_lt_f32_e64 s[0:1], v13, v26
	s_and_b64 s[22:23], s[28:29], s[22:23]
	s_or_b64 s[0:1], s[0:1], s[22:23]
	v_cmp_eq_f32_e64 s[22:23], v10, v26
	v_cndmask_b32_e64 v30, 0, 1, s[0:1]
	v_cmp_lt_f32_e64 s[0:1], v10, v26
	s_and_b64 s[22:23], s[34:35], s[22:23]
	s_or_b64 s[0:1], s[0:1], s[22:23]
	v_cndmask_b32_e64 v31, 0, 1, s[0:1]
	s_movk_i32 s0, 0xffed
	v_cmp_eq_f32_e64 s[26:27], v11, v26
	v_cmp_lt_i32_e64 s[0:1], s0, v32
	v_cmp_lt_f32_e64 s[22:23], v11, v26
	s_and_b64 s[26:27], s[0:1], s[26:27]
	s_movk_i32 s30, 0xffe9
	s_or_b64 s[22:23], s[22:23], s[26:27]
	v_cmp_eq_f32_e64 s[26:27], v16, v26
	v_cmp_lt_i32_e64 s[30:31], s30, v32
	ds_bpermute_b32 v40, v17, v15 offset:64
	v_cndmask_b32_e64 v38, 0, 1, s[22:23]
	v_cmp_lt_f32_e64 s[22:23], v16, v26
	s_and_b64 s[26:27], s[30:31], s[26:27]
	s_movk_i32 s36, 0xffe5
	s_or_b64 s[22:23], s[22:23], s[26:27]
	v_cmp_eq_f32_e64 s[26:27], v9, v26
	v_cmp_lt_i32_e64 s[36:37], s36, v32
	v_cndmask_b32_e64 v39, 0, 1, s[22:23]
	v_cmp_lt_f32_e64 s[22:23], v9, v26
	s_and_b64 s[26:27], s[36:37], s[26:27]
	s_or_b64 s[22:23], s[22:23], s[26:27]
	v_cndmask_b32_e64 v26, 0, 1, s[22:23]
	s_waitcnt lgkmcnt(0)
	v_cmp_eq_f32_e64 s[36:37], v14, v40
	v_cmp_lt_i32_e64 s[22:23], 5, v32
	v_cmp_lt_f32_e64 s[26:27], v14, v40
	s_and_b64 s[36:37], s[22:23], s[36:37]
	s_or_b64 s[26:27], s[26:27], s[36:37]
	v_addc_co_u32_e64 v19, s[26:27], v19, v27, s[26:27]
	v_cmp_eq_f32_e64 s[36:37], v15, v40
	v_cmp_lt_f32_e64 s[26:27], v15, v40
	s_and_b64 s[36:37], s[18:19], s[36:37]
	s_or_b64 s[26:27], s[26:27], s[36:37]
	v_addc_co_u32_e64 v20, s[26:27], v20, v28, s[26:27]
	v_cmp_eq_f32_e64 s[36:37], v12, v40
	v_cmp_lt_f32_e64 s[26:27], v12, v40
	s_and_b64 s[36:37], s[20:21], s[36:37]
	s_or_b64 s[26:27], s[26:27], s[36:37]
	v_addc_co_u32_e64 v21, s[26:27], v21, v29, s[26:27]
	v_cmp_eq_f32_e64 s[36:37], v13, v40
	v_cmp_lt_f32_e64 s[26:27], v13, v40
	s_and_b64 s[36:37], s[24:25], s[36:37]
	s_or_b64 s[26:27], s[26:27], s[36:37]
	v_addc_co_u32_e64 v22, s[26:27], v22, v30, s[26:27]
	v_cmp_eq_f32_e64 s[36:37], v10, v40
	v_cmp_lt_f32_e64 s[26:27], v10, v40
	s_and_b64 s[36:37], s[28:29], s[36:37]
	s_or_b64 s[26:27], s[26:27], s[36:37]
	v_addc_co_u32_e64 v23, s[26:27], v23, v31, s[26:27]
	v_cmp_eq_f32_e64 s[36:37], v11, v40
	v_cmp_lt_f32_e64 s[26:27], v11, v40
	s_and_b64 s[36:37], s[34:35], s[36:37]
	s_or_b64 s[26:27], s[26:27], s[36:37]
	v_addc_co_u32_e64 v24, s[26:27], v24, v38, s[26:27]
	v_cmp_eq_f32_e64 s[36:37], v16, v40
	v_cmp_lt_f32_e64 s[26:27], v16, v40
	s_and_b64 s[36:37], s[0:1], s[36:37]
	s_or_b64 s[26:27], s[26:27], s[36:37]
	v_addc_co_u32_e64 v25, s[26:27], v25, v39, s[26:27]
	v_cmp_eq_f32_e64 s[36:37], v9, v40
	v_cmp_lt_f32_e64 s[26:27], v9, v40
	s_and_b64 s[30:31], s[30:31], s[36:37]
	s_or_b64 s[26:27], s[26:27], s[30:31]
	v_addc_co_u32_e64 v18, s[26:27], v18, v26, s[26:27]
	ds_bpermute_b32 v26, v17, v12 offset:64
	v_cmp_lt_i32_e64 s[26:27], 9, v32
	ds_bpermute_b32 v40, v17, v13 offset:64
	s_waitcnt lgkmcnt(1)
	v_cmp_eq_f32_e64 s[36:37], v14, v26
	v_cmp_lt_f32_e64 s[30:31], v14, v26
	s_and_b64 s[36:37], s[26:27], s[36:37]
	s_or_b64 s[30:31], s[30:31], s[36:37]
	v_cmp_eq_f32_e64 s[36:37], v15, v26
	v_cndmask_b32_e64 v27, 0, 1, s[30:31]
	v_cmp_lt_f32_e64 s[30:31], v15, v26
	s_and_b64 s[36:37], s[22:23], s[36:37]
	s_or_b64 s[30:31], s[30:31], s[36:37]
	v_cmp_eq_f32_e64 s[36:37], v12, v26
	v_cndmask_b32_e64 v28, 0, 1, s[30:31]
	v_cmp_lt_f32_e64 s[30:31], v12, v26
	s_and_b64 s[36:37], s[18:19], s[36:37]
	s_or_b64 s[30:31], s[30:31], s[36:37]
	v_cmp_eq_f32_e64 s[36:37], v13, v26
	v_cndmask_b32_e64 v29, 0, 1, s[30:31]
	v_cmp_lt_f32_e64 s[30:31], v13, v26
	s_and_b64 s[36:37], s[20:21], s[36:37]
	s_or_b64 s[30:31], s[30:31], s[36:37]
	v_cmp_eq_f32_e64 s[36:37], v10, v26
	v_cndmask_b32_e64 v30, 0, 1, s[30:31]
	v_cmp_lt_f32_e64 s[30:31], v10, v26
	s_and_b64 s[36:37], s[24:25], s[36:37]
	s_or_b64 s[30:31], s[30:31], s[36:37]
	v_cmp_eq_f32_e64 s[36:37], v11, v26
	v_cndmask_b32_e64 v31, 0, 1, s[30:31]
	v_cmp_lt_f32_e64 s[30:31], v11, v26
	s_and_b64 s[36:37], s[28:29], s[36:37]
	s_or_b64 s[30:31], s[30:31], s[36:37]
	v_cmp_eq_f32_e64 s[36:37], v16, v26
	v_cndmask_b32_e64 v38, 0, 1, s[30:31]
	v_cmp_lt_f32_e64 s[30:31], v16, v26
	s_and_b64 s[36:37], s[34:35], s[36:37]
	s_or_b64 s[30:31], s[30:31], s[36:37]
	v_cmp_eq_f32_e64 s[36:37], v9, v26
	v_cndmask_b32_e64 v39, 0, 1, s[30:31]
	v_cmp_lt_f32_e64 s[30:31], v9, v26
	s_and_b64 s[0:1], s[0:1], s[36:37]
	s_or_b64 s[0:1], s[30:31], s[0:1]
	s_waitcnt lgkmcnt(0)
	v_cmp_eq_f32_e64 s[36:37], v14, v40
	v_cmp_lt_i32_e64 s[30:31], 13, v32
	v_cndmask_b32_e64 v26, 0, 1, s[0:1]
	v_cmp_lt_f32_e64 s[0:1], v14, v40
	s_and_b64 s[36:37], s[30:31], s[36:37]
	s_or_b64 s[0:1], s[0:1], s[36:37]
	v_addc_co_u32_e64 v19, s[0:1], v19, v27, s[0:1]
	v_cmp_eq_f32_e64 s[36:37], v15, v40
	v_cmp_lt_f32_e64 s[0:1], v15, v40
	s_and_b64 s[36:37], s[26:27], s[36:37]
	s_or_b64 s[0:1], s[0:1], s[36:37]
	v_addc_co_u32_e64 v20, s[0:1], v20, v28, s[0:1]
	v_cmp_eq_f32_e64 s[36:37], v12, v40
	v_cmp_lt_f32_e64 s[0:1], v12, v40
	s_and_b64 s[36:37], s[22:23], s[36:37]
	s_or_b64 s[0:1], s[0:1], s[36:37]
	v_addc_co_u32_e64 v21, s[0:1], v21, v29, s[0:1]
	v_cmp_eq_f32_e64 s[36:37], v13, v40
	v_cmp_lt_f32_e64 s[0:1], v13, v40
	s_and_b64 s[36:37], s[18:19], s[36:37]
	s_or_b64 s[0:1], s[0:1], s[36:37]
	v_addc_co_u32_e64 v22, s[0:1], v22, v30, s[0:1]
	v_cmp_eq_f32_e64 s[36:37], v10, v40
	v_cmp_lt_f32_e64 s[0:1], v10, v40
	s_and_b64 s[36:37], s[20:21], s[36:37]
	s_or_b64 s[0:1], s[0:1], s[36:37]
	v_addc_co_u32_e64 v23, s[0:1], v23, v31, s[0:1]
	v_cmp_eq_f32_e64 s[36:37], v11, v40
	v_cmp_lt_f32_e64 s[0:1], v11, v40
	s_and_b64 s[36:37], s[24:25], s[36:37]
	s_or_b64 s[0:1], s[0:1], s[36:37]
	v_addc_co_u32_e64 v24, s[0:1], v24, v38, s[0:1]
	v_cmp_eq_f32_e64 s[36:37], v16, v40
	v_cmp_lt_f32_e64 s[0:1], v16, v40
	s_and_b64 s[36:37], s[28:29], s[36:37]
	s_or_b64 s[0:1], s[0:1], s[36:37]
	v_addc_co_u32_e64 v25, s[0:1], v25, v39, s[0:1]
	v_cmp_eq_f32_e64 s[36:37], v9, v40
	v_cmp_lt_f32_e64 s[0:1], v9, v40
	s_and_b64 s[34:35], s[34:35], s[36:37]
	s_or_b64 s[0:1], s[0:1], s[34:35]
	v_addc_co_u32_e64 v18, s[0:1], v18, v26, s[0:1]
	ds_bpermute_b32 v26, v17, v10 offset:64
	v_cmp_lt_i32_e64 s[34:35], 17, v32
	ds_bpermute_b32 v40, v17, v11 offset:64
	s_waitcnt lgkmcnt(1)
	v_cmp_eq_f32_e64 s[36:37], v14, v26
	v_cmp_lt_f32_e64 s[0:1], v14, v26
	s_and_b64 s[36:37], s[34:35], s[36:37]
	s_or_b64 s[0:1], s[0:1], s[36:37]
	v_cmp_eq_f32_e64 s[36:37], v15, v26
	v_cndmask_b32_e64 v27, 0, 1, s[0:1]
	v_cmp_lt_f32_e64 s[0:1], v15, v26
	s_and_b64 s[36:37], s[30:31], s[36:37]
	s_or_b64 s[0:1], s[0:1], s[36:37]
	v_cmp_eq_f32_e64 s[36:37], v12, v26
	v_cndmask_b32_e64 v28, 0, 1, s[0:1]
	v_cmp_lt_f32_e64 s[0:1], v12, v26
	s_and_b64 s[36:37], s[26:27], s[36:37]
	s_or_b64 s[0:1], s[0:1], s[36:37]
	v_cmp_eq_f32_e64 s[36:37], v13, v26
	v_cndmask_b32_e64 v29, 0, 1, s[0:1]
	v_cmp_lt_f32_e64 s[0:1], v13, v26
	s_and_b64 s[36:37], s[22:23], s[36:37]
	s_or_b64 s[0:1], s[0:1], s[36:37]
	v_cmp_eq_f32_e64 s[36:37], v10, v26
	v_cndmask_b32_e64 v30, 0, 1, s[0:1]
	v_cmp_lt_f32_e64 s[0:1], v10, v26
	s_and_b64 s[36:37], s[18:19], s[36:37]
	s_or_b64 s[0:1], s[0:1], s[36:37]
	v_cmp_eq_f32_e64 s[36:37], v11, v26
	v_cndmask_b32_e64 v31, 0, 1, s[0:1]
	v_cmp_lt_f32_e64 s[0:1], v11, v26
	s_and_b64 s[36:37], s[20:21], s[36:37]
	s_or_b64 s[0:1], s[0:1], s[36:37]
	v_cmp_eq_f32_e64 s[36:37], v16, v26
	v_cndmask_b32_e64 v38, 0, 1, s[0:1]
	v_cmp_lt_f32_e64 s[0:1], v16, v26
	s_and_b64 s[36:37], s[24:25], s[36:37]
	s_or_b64 s[0:1], s[0:1], s[36:37]
	v_cmp_eq_f32_e64 s[36:37], v9, v26
	v_cndmask_b32_e64 v39, 0, 1, s[0:1]
	v_cmp_lt_f32_e64 s[0:1], v9, v26
	s_and_b64 s[28:29], s[28:29], s[36:37]
	s_or_b64 s[0:1], s[0:1], s[28:29]
	v_cndmask_b32_e64 v26, 0, 1, s[0:1]
	s_waitcnt lgkmcnt(0)
	v_cmp_eq_f32_e64 s[36:37], v14, v40
	v_cmp_lt_i32_e64 s[0:1], 21, v32
	v_cmp_lt_f32_e64 s[28:29], v14, v40
	s_and_b64 s[36:37], s[0:1], s[36:37]
	s_or_b64 s[28:29], s[28:29], s[36:37]
	v_addc_co_u32_e64 v19, s[28:29], v19, v27, s[28:29]
	v_cmp_eq_f32_e64 s[36:37], v15, v40
	v_cmp_lt_f32_e64 s[28:29], v15, v40
	s_and_b64 s[36:37], s[34:35], s[36:37]
	s_or_b64 s[28:29], s[28:29], s[36:37]
	v_addc_co_u32_e64 v20, s[28:29], v20, v28, s[28:29]
	v_cmp_eq_f32_e64 s[36:37], v12, v40
	v_cmp_lt_f32_e64 s[28:29], v12, v40
	s_and_b64 s[36:37], s[30:31], s[36:37]
	s_or_b64 s[28:29], s[28:29], s[36:37]
	v_addc_co_u32_e64 v21, s[28:29], v21, v29, s[28:29]
	v_cmp_eq_f32_e64 s[36:37], v13, v40
	v_cmp_lt_f32_e64 s[28:29], v13, v40
	s_and_b64 s[36:37], s[26:27], s[36:37]
	s_or_b64 s[28:29], s[28:29], s[36:37]
	v_addc_co_u32_e64 v22, s[28:29], v22, v30, s[28:29]
	v_cmp_eq_f32_e64 s[36:37], v10, v40
	v_cmp_lt_f32_e64 s[28:29], v10, v40
	s_and_b64 s[36:37], s[22:23], s[36:37]
	s_or_b64 s[28:29], s[28:29], s[36:37]
	v_addc_co_u32_e64 v23, s[28:29], v23, v31, s[28:29]
	v_cmp_eq_f32_e64 s[36:37], v11, v40
	v_cmp_lt_f32_e64 s[28:29], v11, v40
	s_and_b64 s[36:37], s[18:19], s[36:37]
	s_or_b64 s[28:29], s[28:29], s[36:37]
	v_addc_co_u32_e64 v24, s[28:29], v24, v38, s[28:29]
	v_cmp_eq_f32_e64 s[36:37], v16, v40
	v_cmp_lt_f32_e64 s[28:29], v16, v40
	s_and_b64 s[36:37], s[20:21], s[36:37]
	s_or_b64 s[28:29], s[28:29], s[36:37]
	v_addc_co_u32_e64 v25, s[28:29], v25, v39, s[28:29]
	v_cmp_eq_f32_e64 s[36:37], v9, v40
	v_cmp_lt_f32_e64 s[28:29], v9, v40
	s_and_b64 s[24:25], s[24:25], s[36:37]
	s_or_b64 s[24:25], s[28:29], s[24:25]
	v_addc_co_u32_e64 v18, s[24:25], v18, v26, s[24:25]
	ds_bpermute_b32 v26, v17, v16 offset:64
	v_cmp_lt_i32_e64 s[36:37], 25, v32
	ds_bpermute_b32 v40, v17, v9 offset:64
	s_waitcnt lgkmcnt(1)
	v_cmp_eq_f32_e64 s[28:29], v14, v26
	v_cmp_lt_f32_e64 s[24:25], v14, v26
	s_and_b64 s[28:29], s[36:37], s[28:29]
	s_or_b64 s[24:25], s[24:25], s[28:29]
	v_cmp_eq_f32_e64 s[28:29], v15, v26
	v_cndmask_b32_e64 v27, 0, 1, s[24:25]
	v_cmp_lt_f32_e64 s[24:25], v15, v26
	s_and_b64 s[28:29], s[0:1], s[28:29]
	s_or_b64 s[24:25], s[24:25], s[28:29]
	v_cmp_eq_f32_e64 s[28:29], v12, v26
	v_cndmask_b32_e64 v28, 0, 1, s[24:25]
	v_cmp_lt_f32_e64 s[24:25], v12, v26
	s_and_b64 s[28:29], s[34:35], s[28:29]
	s_or_b64 s[24:25], s[24:25], s[28:29]
	v_cmp_eq_f32_e64 s[28:29], v13, v26
	v_cndmask_b32_e64 v29, 0, 1, s[24:25]
	v_cmp_lt_f32_e64 s[24:25], v13, v26
	s_and_b64 s[28:29], s[30:31], s[28:29]
	s_or_b64 s[24:25], s[24:25], s[28:29]
	v_cmp_eq_f32_e64 s[28:29], v10, v26
	v_cndmask_b32_e64 v30, 0, 1, s[24:25]
	v_cmp_lt_f32_e64 s[24:25], v10, v26
	s_and_b64 s[28:29], s[26:27], s[28:29]
	s_or_b64 s[24:25], s[24:25], s[28:29]
	v_cmp_eq_f32_e64 s[28:29], v11, v26
	v_cndmask_b32_e64 v31, 0, 1, s[24:25]
	v_cmp_lt_f32_e64 s[24:25], v11, v26
	s_and_b64 s[28:29], s[22:23], s[28:29]
	s_or_b64 s[24:25], s[24:25], s[28:29]
	v_cmp_eq_f32_e64 s[28:29], v16, v26
	v_cndmask_b32_e64 v38, 0, 1, s[24:25]
	v_cmp_lt_f32_e64 s[24:25], v16, v26
	s_and_b64 s[28:29], s[18:19], s[28:29]
	s_or_b64 s[24:25], s[24:25], s[28:29]
	v_cmp_eq_f32_e64 s[28:29], v9, v26
	v_cndmask_b32_e64 v39, 0, 1, s[24:25]
	v_cmp_lt_f32_e64 s[24:25], v9, v26
	s_and_b64 s[20:21], s[20:21], s[28:29]
	s_or_b64 s[20:21], s[24:25], s[20:21]
	s_waitcnt lgkmcnt(0)
	v_cmp_eq_f32_e64 s[24:25], v14, v40
	v_cmp_lt_i32_e64 s[28:29], 29, v32
	v_cndmask_b32_e64 v26, 0, 1, s[20:21]
	v_cmp_lt_f32_e64 s[20:21], v14, v40
	s_and_b64 s[24:25], s[28:29], s[24:25]
	s_or_b64 s[20:21], s[20:21], s[24:25]
	v_addc_co_u32_e64 v19, s[20:21], v19, v27, s[20:21]
	v_cmp_eq_f32_e64 s[24:25], v15, v40
	v_cmp_lt_f32_e64 s[20:21], v15, v40
	s_and_b64 s[24:25], s[36:37], s[24:25]
	s_or_b64 s[20:21], s[20:21], s[24:25]
	v_addc_co_u32_e64 v20, s[20:21], v20, v28, s[20:21]
	v_cmp_eq_f32_e64 s[24:25], v12, v40
	v_cmp_lt_f32_e64 s[20:21], v12, v40
	s_and_b64 s[0:1], s[0:1], s[24:25]
	s_or_b64 s[0:1], s[20:21], s[0:1]
	v_addc_co_u32_e64 v21, s[0:1], v21, v29, s[0:1]
	v_cmp_eq_f32_e64 s[20:21], v13, v40
	v_cmp_lt_f32_e64 s[0:1], v13, v40
	s_and_b64 s[20:21], s[34:35], s[20:21]
	s_or_b64 s[0:1], s[0:1], s[20:21]
	v_addc_co_u32_e64 v22, s[0:1], v22, v30, s[0:1]
	v_cmp_eq_f32_e64 s[20:21], v10, v40
	v_cmp_lt_f32_e64 s[0:1], v10, v40
	s_and_b64 s[20:21], s[30:31], s[20:21]
	s_or_b64 s[0:1], s[0:1], s[20:21]
	v_addc_co_u32_e64 v23, s[0:1], v23, v31, s[0:1]
	v_cmp_eq_f32_e64 s[20:21], v11, v40
	v_cmp_lt_f32_e64 s[0:1], v11, v40
	s_and_b64 s[20:21], s[26:27], s[20:21]
	s_or_b64 s[0:1], s[0:1], s[20:21]
	v_addc_co_u32_e64 v24, s[0:1], v24, v38, s[0:1]
	v_cmp_eq_f32_e64 s[20:21], v16, v40
	v_cmp_lt_f32_e64 s[0:1], v16, v40
	s_and_b64 s[20:21], s[22:23], s[20:21]
	s_or_b64 s[0:1], s[0:1], s[20:21]
	v_addc_co_u32_e64 v25, s[0:1], v25, v39, s[0:1]
	v_cmp_eq_f32_e64 s[20:21], v9, v40
	v_cmp_lt_f32_e64 s[0:1], v9, v40
	s_and_b64 s[18:19], s[18:19], s[20:21]
	s_or_b64 s[0:1], s[0:1], s[18:19]
	v_addc_co_u32_e64 v18, s[0:1], v18, v26, s[0:1]
	ds_bpermute_b32 v26, v17, v14 offset:128
	v_cmp_lt_i32_e64 s[18:19], 2, v32
	v_cmp_lt_i32_e64 s[24:25], -6, v32
	v_cmp_lt_i32_e64 s[28:29], -10, v32
	v_cmp_lt_i32_e64 s[34:35], -14, v32
	s_waitcnt lgkmcnt(0)
	v_cmp_eq_f32_e64 s[20:21], v14, v26
	v_cmp_lt_f32_e64 s[0:1], v14, v26
	s_and_b64 s[20:21], s[18:19], s[20:21]
	s_or_b64 s[0:1], s[0:1], s[20:21]
	v_cmp_eq_f32_e64 s[22:23], v15, v26
	v_cmp_lt_i32_e64 s[20:21], -2, v32
	v_cndmask_b32_e64 v27, 0, 1, s[0:1]
	v_cmp_lt_f32_e64 s[0:1], v15, v26
	s_and_b64 s[22:23], s[20:21], s[22:23]
	s_or_b64 s[0:1], s[0:1], s[22:23]
	v_cmp_eq_f32_e64 s[22:23], v12, v26
	v_cndmask_b32_e64 v28, 0, 1, s[0:1]
	v_cmp_lt_f32_e64 s[0:1], v12, v26
	s_and_b64 s[22:23], s[24:25], s[22:23]
	s_or_b64 s[0:1], s[0:1], s[22:23]
	v_cmp_eq_f32_e64 s[22:23], v13, v26
	v_cndmask_b32_e64 v29, 0, 1, s[0:1]
	v_cmp_lt_f32_e64 s[0:1], v13, v26
	s_and_b64 s[22:23], s[28:29], s[22:23]
	s_or_b64 s[0:1], s[0:1], s[22:23]
	v_cmp_eq_f32_e64 s[22:23], v10, v26
	v_cndmask_b32_e64 v30, 0, 1, s[0:1]
	v_cmp_lt_f32_e64 s[0:1], v10, v26
	s_and_b64 s[22:23], s[34:35], s[22:23]
	s_or_b64 s[0:1], s[0:1], s[22:23]
	v_cndmask_b32_e64 v31, 0, 1, s[0:1]
	s_movk_i32 s0, 0xffee
	v_cmp_eq_f32_e64 s[26:27], v11, v26
	v_cmp_lt_i32_e64 s[0:1], s0, v32
	v_cmp_lt_f32_e64 s[22:23], v11, v26
	s_and_b64 s[26:27], s[0:1], s[26:27]
	s_movk_i32 s30, 0xffea
	s_or_b64 s[22:23], s[22:23], s[26:27]
	v_cmp_eq_f32_e64 s[26:27], v16, v26
	v_cmp_lt_i32_e64 s[30:31], s30, v32
	ds_bpermute_b32 v40, v17, v15 offset:128
	v_cndmask_b32_e64 v38, 0, 1, s[22:23]
	v_cmp_lt_f32_e64 s[22:23], v16, v26
	s_and_b64 s[26:27], s[30:31], s[26:27]
	s_movk_i32 s36, 0xffe6
	s_or_b64 s[22:23], s[22:23], s[26:27]
	v_cmp_eq_f32_e64 s[26:27], v9, v26
	v_cmp_lt_i32_e64 s[36:37], s36, v32
	v_cndmask_b32_e64 v39, 0, 1, s[22:23]
	v_cmp_lt_f32_e64 s[22:23], v9, v26
	s_and_b64 s[26:27], s[36:37], s[26:27]
	s_or_b64 s[22:23], s[22:23], s[26:27]
	v_cndmask_b32_e64 v26, 0, 1, s[22:23]
	s_waitcnt lgkmcnt(0)
	v_cmp_eq_f32_e64 s[36:37], v14, v40
	v_cmp_lt_i32_e64 s[22:23], 6, v32
	v_cmp_lt_f32_e64 s[26:27], v14, v40
	s_and_b64 s[36:37], s[22:23], s[36:37]
	s_or_b64 s[26:27], s[26:27], s[36:37]
	v_addc_co_u32_e64 v19, s[26:27], v19, v27, s[26:27]
	v_cmp_eq_f32_e64 s[36:37], v15, v40
	v_cmp_lt_f32_e64 s[26:27], v15, v40
	s_and_b64 s[36:37], s[18:19], s[36:37]
	s_or_b64 s[26:27], s[26:27], s[36:37]
	v_addc_co_u32_e64 v20, s[26:27], v20, v28, s[26:27]
	v_cmp_eq_f32_e64 s[36:37], v12, v40
	v_cmp_lt_f32_e64 s[26:27], v12, v40
	s_and_b64 s[36:37], s[20:21], s[36:37]
	s_or_b64 s[26:27], s[26:27], s[36:37]
	v_addc_co_u32_e64 v21, s[26:27], v21, v29, s[26:27]
	v_cmp_eq_f32_e64 s[36:37], v13, v40
	v_cmp_lt_f32_e64 s[26:27], v13, v40
	s_and_b64 s[36:37], s[24:25], s[36:37]
	s_or_b64 s[26:27], s[26:27], s[36:37]
	v_addc_co_u32_e64 v22, s[26:27], v22, v30, s[26:27]
	v_cmp_eq_f32_e64 s[36:37], v10, v40
	v_cmp_lt_f32_e64 s[26:27], v10, v40
	s_and_b64 s[36:37], s[28:29], s[36:37]
	s_or_b64 s[26:27], s[26:27], s[36:37]
	v_addc_co_u32_e64 v23, s[26:27], v23, v31, s[26:27]
	v_cmp_eq_f32_e64 s[36:37], v11, v40
	v_cmp_lt_f32_e64 s[26:27], v11, v40
	s_and_b64 s[36:37], s[34:35], s[36:37]
	s_or_b64 s[26:27], s[26:27], s[36:37]
	v_addc_co_u32_e64 v24, s[26:27], v24, v38, s[26:27]
	v_cmp_eq_f32_e64 s[36:37], v16, v40
	v_cmp_lt_f32_e64 s[26:27], v16, v40
	s_and_b64 s[36:37], s[0:1], s[36:37]
	s_or_b64 s[26:27], s[26:27], s[36:37]
	v_addc_co_u32_e64 v25, s[26:27], v25, v39, s[26:27]
	v_cmp_eq_f32_e64 s[36:37], v9, v40
	v_cmp_lt_f32_e64 s[26:27], v9, v40
	s_and_b64 s[30:31], s[30:31], s[36:37]
	s_or_b64 s[26:27], s[26:27], s[30:31]
	v_addc_co_u32_e64 v18, s[26:27], v18, v26, s[26:27]
	ds_bpermute_b32 v26, v17, v12 offset:128
	v_cmp_lt_i32_e64 s[26:27], 10, v32
	ds_bpermute_b32 v40, v17, v13 offset:128
	s_waitcnt lgkmcnt(1)
	v_cmp_eq_f32_e64 s[36:37], v14, v26
	v_cmp_lt_f32_e64 s[30:31], v14, v26
	s_and_b64 s[36:37], s[26:27], s[36:37]
	s_or_b64 s[30:31], s[30:31], s[36:37]
	v_cmp_eq_f32_e64 s[36:37], v15, v26
	v_cndmask_b32_e64 v27, 0, 1, s[30:31]
	v_cmp_lt_f32_e64 s[30:31], v15, v26
	s_and_b64 s[36:37], s[22:23], s[36:37]
	s_or_b64 s[30:31], s[30:31], s[36:37]
	v_cmp_eq_f32_e64 s[36:37], v12, v26
	v_cndmask_b32_e64 v28, 0, 1, s[30:31]
	v_cmp_lt_f32_e64 s[30:31], v12, v26
	s_and_b64 s[36:37], s[18:19], s[36:37]
	s_or_b64 s[30:31], s[30:31], s[36:37]
	v_cmp_eq_f32_e64 s[36:37], v13, v26
	v_cndmask_b32_e64 v29, 0, 1, s[30:31]
	v_cmp_lt_f32_e64 s[30:31], v13, v26
	s_and_b64 s[36:37], s[20:21], s[36:37]
	s_or_b64 s[30:31], s[30:31], s[36:37]
	v_cmp_eq_f32_e64 s[36:37], v10, v26
	v_cndmask_b32_e64 v30, 0, 1, s[30:31]
	v_cmp_lt_f32_e64 s[30:31], v10, v26
	s_and_b64 s[36:37], s[24:25], s[36:37]
	s_or_b64 s[30:31], s[30:31], s[36:37]
	v_cmp_eq_f32_e64 s[36:37], v11, v26
	v_cndmask_b32_e64 v31, 0, 1, s[30:31]
	v_cmp_lt_f32_e64 s[30:31], v11, v26
	s_and_b64 s[36:37], s[28:29], s[36:37]
	s_or_b64 s[30:31], s[30:31], s[36:37]
	v_cmp_eq_f32_e64 s[36:37], v16, v26
	v_cndmask_b32_e64 v38, 0, 1, s[30:31]
	v_cmp_lt_f32_e64 s[30:31], v16, v26
	s_and_b64 s[36:37], s[34:35], s[36:37]
	s_or_b64 s[30:31], s[30:31], s[36:37]
	v_cmp_eq_f32_e64 s[36:37], v9, v26
	v_cndmask_b32_e64 v39, 0, 1, s[30:31]
	v_cmp_lt_f32_e64 s[30:31], v9, v26
	s_and_b64 s[0:1], s[0:1], s[36:37]
	s_or_b64 s[0:1], s[30:31], s[0:1]
	s_waitcnt lgkmcnt(0)
	v_cmp_eq_f32_e64 s[36:37], v14, v40
	v_cmp_lt_i32_e64 s[30:31], 14, v32
	v_cndmask_b32_e64 v26, 0, 1, s[0:1]
	v_cmp_lt_f32_e64 s[0:1], v14, v40
	s_and_b64 s[36:37], s[30:31], s[36:37]
	s_or_b64 s[0:1], s[0:1], s[36:37]
	v_addc_co_u32_e64 v19, s[0:1], v19, v27, s[0:1]
	v_cmp_eq_f32_e64 s[36:37], v15, v40
	v_cmp_lt_f32_e64 s[0:1], v15, v40
	s_and_b64 s[36:37], s[26:27], s[36:37]
	s_or_b64 s[0:1], s[0:1], s[36:37]
	v_addc_co_u32_e64 v20, s[0:1], v20, v28, s[0:1]
	v_cmp_eq_f32_e64 s[36:37], v12, v40
	v_cmp_lt_f32_e64 s[0:1], v12, v40
	s_and_b64 s[36:37], s[22:23], s[36:37]
	s_or_b64 s[0:1], s[0:1], s[36:37]
	v_addc_co_u32_e64 v21, s[0:1], v21, v29, s[0:1]
	v_cmp_eq_f32_e64 s[36:37], v13, v40
	v_cmp_lt_f32_e64 s[0:1], v13, v40
	s_and_b64 s[36:37], s[18:19], s[36:37]
	s_or_b64 s[0:1], s[0:1], s[36:37]
	v_addc_co_u32_e64 v22, s[0:1], v22, v30, s[0:1]
	v_cmp_eq_f32_e64 s[36:37], v10, v40
	v_cmp_lt_f32_e64 s[0:1], v10, v40
	s_and_b64 s[36:37], s[20:21], s[36:37]
	s_or_b64 s[0:1], s[0:1], s[36:37]
	v_addc_co_u32_e64 v23, s[0:1], v23, v31, s[0:1]
	v_cmp_eq_f32_e64 s[36:37], v11, v40
	v_cmp_lt_f32_e64 s[0:1], v11, v40
	s_and_b64 s[36:37], s[24:25], s[36:37]
	s_or_b64 s[0:1], s[0:1], s[36:37]
	v_addc_co_u32_e64 v24, s[0:1], v24, v38, s[0:1]
	v_cmp_eq_f32_e64 s[36:37], v16, v40
	v_cmp_lt_f32_e64 s[0:1], v16, v40
	s_and_b64 s[36:37], s[28:29], s[36:37]
	s_or_b64 s[0:1], s[0:1], s[36:37]
	v_addc_co_u32_e64 v25, s[0:1], v25, v39, s[0:1]
	v_cmp_eq_f32_e64 s[36:37], v9, v40
	v_cmp_lt_f32_e64 s[0:1], v9, v40
	s_and_b64 s[34:35], s[34:35], s[36:37]
	s_or_b64 s[0:1], s[0:1], s[34:35]
	v_addc_co_u32_e64 v18, s[0:1], v18, v26, s[0:1]
	ds_bpermute_b32 v26, v17, v10 offset:128
	v_cmp_lt_i32_e64 s[34:35], 18, v32
	ds_bpermute_b32 v40, v17, v11 offset:128
	s_waitcnt lgkmcnt(1)
	v_cmp_eq_f32_e64 s[36:37], v14, v26
	v_cmp_lt_f32_e64 s[0:1], v14, v26
	s_and_b64 s[36:37], s[34:35], s[36:37]
	s_or_b64 s[0:1], s[0:1], s[36:37]
	v_cmp_eq_f32_e64 s[36:37], v15, v26
	v_cndmask_b32_e64 v27, 0, 1, s[0:1]
	v_cmp_lt_f32_e64 s[0:1], v15, v26
	s_and_b64 s[36:37], s[30:31], s[36:37]
	s_or_b64 s[0:1], s[0:1], s[36:37]
	v_cmp_eq_f32_e64 s[36:37], v12, v26
	v_cndmask_b32_e64 v28, 0, 1, s[0:1]
	v_cmp_lt_f32_e64 s[0:1], v12, v26
	s_and_b64 s[36:37], s[26:27], s[36:37]
	s_or_b64 s[0:1], s[0:1], s[36:37]
	v_cmp_eq_f32_e64 s[36:37], v13, v26
	v_cndmask_b32_e64 v29, 0, 1, s[0:1]
	v_cmp_lt_f32_e64 s[0:1], v13, v26
	s_and_b64 s[36:37], s[22:23], s[36:37]
	s_or_b64 s[0:1], s[0:1], s[36:37]
	v_cmp_eq_f32_e64 s[36:37], v10, v26
	v_cndmask_b32_e64 v30, 0, 1, s[0:1]
	v_cmp_lt_f32_e64 s[0:1], v10, v26
	s_and_b64 s[36:37], s[18:19], s[36:37]
	s_or_b64 s[0:1], s[0:1], s[36:37]
	v_cmp_eq_f32_e64 s[36:37], v11, v26
	v_cndmask_b32_e64 v31, 0, 1, s[0:1]
	v_cmp_lt_f32_e64 s[0:1], v11, v26
	s_and_b64 s[36:37], s[20:21], s[36:37]
	s_or_b64 s[0:1], s[0:1], s[36:37]
	v_cmp_eq_f32_e64 s[36:37], v16, v26
	v_cndmask_b32_e64 v38, 0, 1, s[0:1]
	v_cmp_lt_f32_e64 s[0:1], v16, v26
	s_and_b64 s[36:37], s[24:25], s[36:37]
	s_or_b64 s[0:1], s[0:1], s[36:37]
	v_cmp_eq_f32_e64 s[36:37], v9, v26
	v_cndmask_b32_e64 v39, 0, 1, s[0:1]
	v_cmp_lt_f32_e64 s[0:1], v9, v26
	s_and_b64 s[28:29], s[28:29], s[36:37]
	s_or_b64 s[0:1], s[0:1], s[28:29]
	v_cndmask_b32_e64 v26, 0, 1, s[0:1]
	s_waitcnt lgkmcnt(0)
	v_cmp_eq_f32_e64 s[36:37], v14, v40
	v_cmp_lt_i32_e64 s[0:1], 22, v32
	v_cmp_lt_f32_e64 s[28:29], v14, v40
	s_and_b64 s[36:37], s[0:1], s[36:37]
	s_or_b64 s[28:29], s[28:29], s[36:37]
	v_addc_co_u32_e64 v19, s[28:29], v19, v27, s[28:29]
	v_cmp_eq_f32_e64 s[36:37], v15, v40
	v_cmp_lt_f32_e64 s[28:29], v15, v40
	s_and_b64 s[36:37], s[34:35], s[36:37]
	s_or_b64 s[28:29], s[28:29], s[36:37]
	v_addc_co_u32_e64 v20, s[28:29], v20, v28, s[28:29]
	v_cmp_eq_f32_e64 s[36:37], v12, v40
	v_cmp_lt_f32_e64 s[28:29], v12, v40
	s_and_b64 s[36:37], s[30:31], s[36:37]
	s_or_b64 s[28:29], s[28:29], s[36:37]
	v_addc_co_u32_e64 v21, s[28:29], v21, v29, s[28:29]
	v_cmp_eq_f32_e64 s[36:37], v13, v40
	v_cmp_lt_f32_e64 s[28:29], v13, v40
	s_and_b64 s[36:37], s[26:27], s[36:37]
	s_or_b64 s[28:29], s[28:29], s[36:37]
	v_addc_co_u32_e64 v22, s[28:29], v22, v30, s[28:29]
	v_cmp_eq_f32_e64 s[36:37], v10, v40
	v_cmp_lt_f32_e64 s[28:29], v10, v40
	s_and_b64 s[36:37], s[22:23], s[36:37]
	s_or_b64 s[28:29], s[28:29], s[36:37]
	v_addc_co_u32_e64 v23, s[28:29], v23, v31, s[28:29]
	v_cmp_eq_f32_e64 s[36:37], v11, v40
	v_cmp_lt_f32_e64 s[28:29], v11, v40
	s_and_b64 s[36:37], s[18:19], s[36:37]
	s_or_b64 s[28:29], s[28:29], s[36:37]
	v_addc_co_u32_e64 v24, s[28:29], v24, v38, s[28:29]
	v_cmp_eq_f32_e64 s[36:37], v16, v40
	v_cmp_lt_f32_e64 s[28:29], v16, v40
	s_and_b64 s[36:37], s[20:21], s[36:37]
	s_or_b64 s[28:29], s[28:29], s[36:37]
	v_addc_co_u32_e64 v25, s[28:29], v25, v39, s[28:29]
	v_cmp_eq_f32_e64 s[36:37], v9, v40
	v_cmp_lt_f32_e64 s[28:29], v9, v40
	s_and_b64 s[24:25], s[24:25], s[36:37]
	s_or_b64 s[24:25], s[28:29], s[24:25]
	v_addc_co_u32_e64 v18, s[24:25], v18, v26, s[24:25]
	ds_bpermute_b32 v26, v17, v16 offset:128
	v_cmp_lt_i32_e64 s[36:37], 26, v32
	ds_bpermute_b32 v40, v17, v9 offset:128
	s_waitcnt lgkmcnt(1)
	v_cmp_eq_f32_e64 s[28:29], v14, v26
	v_cmp_lt_f32_e64 s[24:25], v14, v26
	s_and_b64 s[28:29], s[36:37], s[28:29]
	s_or_b64 s[24:25], s[24:25], s[28:29]
	v_cmp_eq_f32_e64 s[28:29], v15, v26
	v_cndmask_b32_e64 v27, 0, 1, s[24:25]
	v_cmp_lt_f32_e64 s[24:25], v15, v26
	s_and_b64 s[28:29], s[0:1], s[28:29]
	s_or_b64 s[24:25], s[24:25], s[28:29]
	v_cmp_eq_f32_e64 s[28:29], v12, v26
	v_cndmask_b32_e64 v28, 0, 1, s[24:25]
	v_cmp_lt_f32_e64 s[24:25], v12, v26
	s_and_b64 s[28:29], s[34:35], s[28:29]
	s_or_b64 s[24:25], s[24:25], s[28:29]
	v_cmp_eq_f32_e64 s[28:29], v13, v26
	v_cndmask_b32_e64 v29, 0, 1, s[24:25]
	v_cmp_lt_f32_e64 s[24:25], v13, v26
	s_and_b64 s[28:29], s[30:31], s[28:29]
	s_or_b64 s[24:25], s[24:25], s[28:29]
	v_cmp_eq_f32_e64 s[28:29], v10, v26
	v_cndmask_b32_e64 v30, 0, 1, s[24:25]
	v_cmp_lt_f32_e64 s[24:25], v10, v26
	s_and_b64 s[28:29], s[26:27], s[28:29]
	s_or_b64 s[24:25], s[24:25], s[28:29]
	v_cmp_eq_f32_e64 s[28:29], v11, v26
	v_cndmask_b32_e64 v31, 0, 1, s[24:25]
	v_cmp_lt_f32_e64 s[24:25], v11, v26
	s_and_b64 s[28:29], s[22:23], s[28:29]
	s_or_b64 s[24:25], s[24:25], s[28:29]
	v_cmp_eq_f32_e64 s[28:29], v16, v26
	v_cndmask_b32_e64 v38, 0, 1, s[24:25]
	v_cmp_lt_f32_e64 s[24:25], v16, v26
	s_and_b64 s[28:29], s[18:19], s[28:29]
	s_or_b64 s[24:25], s[24:25], s[28:29]
	v_cmp_eq_f32_e64 s[28:29], v9, v26
	v_cndmask_b32_e64 v39, 0, 1, s[24:25]
	v_cmp_lt_f32_e64 s[24:25], v9, v26
	s_and_b64 s[20:21], s[20:21], s[28:29]
	s_or_b64 s[20:21], s[24:25], s[20:21]
	s_waitcnt lgkmcnt(0)
	v_cmp_eq_f32_e64 s[24:25], v14, v40
	v_cmp_lt_i32_e64 s[28:29], 30, v32
	v_cndmask_b32_e64 v26, 0, 1, s[20:21]
	v_cmp_lt_f32_e64 s[20:21], v14, v40
	s_and_b64 s[24:25], s[28:29], s[24:25]
	s_or_b64 s[20:21], s[20:21], s[24:25]
	v_addc_co_u32_e64 v19, s[20:21], v19, v27, s[20:21]
	v_cmp_eq_f32_e64 s[24:25], v15, v40
	v_cmp_lt_f32_e64 s[20:21], v15, v40
	s_and_b64 s[24:25], s[36:37], s[24:25]
	s_or_b64 s[20:21], s[20:21], s[24:25]
	v_addc_co_u32_e64 v20, s[20:21], v20, v28, s[20:21]
	v_cmp_eq_f32_e64 s[24:25], v12, v40
	v_cmp_lt_f32_e64 s[20:21], v12, v40
	s_and_b64 s[0:1], s[0:1], s[24:25]
	s_or_b64 s[0:1], s[20:21], s[0:1]
	v_addc_co_u32_e64 v21, s[0:1], v21, v29, s[0:1]
	v_cmp_eq_f32_e64 s[20:21], v13, v40
	v_cmp_lt_f32_e64 s[0:1], v13, v40
	s_and_b64 s[20:21], s[34:35], s[20:21]
	s_or_b64 s[0:1], s[0:1], s[20:21]
	v_addc_co_u32_e64 v22, s[0:1], v22, v30, s[0:1]
	v_cmp_eq_f32_e64 s[20:21], v10, v40
	v_cmp_lt_f32_e64 s[0:1], v10, v40
	s_and_b64 s[20:21], s[30:31], s[20:21]
	s_or_b64 s[0:1], s[0:1], s[20:21]
	v_addc_co_u32_e64 v23, s[0:1], v23, v31, s[0:1]
	v_cmp_eq_f32_e64 s[20:21], v11, v40
	v_cmp_lt_f32_e64 s[0:1], v11, v40
	s_and_b64 s[20:21], s[26:27], s[20:21]
	s_or_b64 s[0:1], s[0:1], s[20:21]
	v_addc_co_u32_e64 v24, s[0:1], v24, v38, s[0:1]
	v_cmp_eq_f32_e64 s[20:21], v16, v40
	v_cmp_lt_f32_e64 s[0:1], v16, v40
	s_and_b64 s[20:21], s[22:23], s[20:21]
	s_or_b64 s[0:1], s[0:1], s[20:21]
	v_addc_co_u32_e64 v25, s[0:1], v25, v39, s[0:1]
	v_cmp_eq_f32_e64 s[20:21], v9, v40
	v_cmp_lt_f32_e64 s[0:1], v9, v40
	s_and_b64 s[18:19], s[18:19], s[20:21]
	s_or_b64 s[0:1], s[0:1], s[18:19]
	v_addc_co_u32_e64 v18, s[0:1], v18, v26, s[0:1]
	ds_bpermute_b32 v26, v17, v14 offset:192
	v_cmp_lt_i32_e64 s[18:19], 3, v32
	v_cmp_lt_i32_e64 s[24:25], -5, v32
	v_cmp_lt_i32_e64 s[28:29], -9, v32
	v_cmp_lt_i32_e64 s[34:35], -13, v32
	s_waitcnt lgkmcnt(0)
	v_cmp_eq_f32_e64 s[20:21], v14, v26
	v_cmp_lt_f32_e64 s[0:1], v14, v26
	s_and_b64 s[20:21], s[18:19], s[20:21]
	s_or_b64 s[0:1], s[0:1], s[20:21]
	v_cmp_eq_f32_e64 s[22:23], v15, v26
	v_cmp_lt_i32_e64 s[20:21], -1, v32
	v_cndmask_b32_e64 v27, 0, 1, s[0:1]
	v_cmp_lt_f32_e64 s[0:1], v15, v26
	s_and_b64 s[22:23], s[20:21], s[22:23]
	s_or_b64 s[0:1], s[0:1], s[22:23]
	v_cmp_eq_f32_e64 s[22:23], v12, v26
	v_cndmask_b32_e64 v28, 0, 1, s[0:1]
	v_cmp_lt_f32_e64 s[0:1], v12, v26
	s_and_b64 s[22:23], s[24:25], s[22:23]
	s_or_b64 s[0:1], s[0:1], s[22:23]
	v_cmp_eq_f32_e64 s[22:23], v13, v26
	v_cndmask_b32_e64 v29, 0, 1, s[0:1]
	v_cmp_lt_f32_e64 s[0:1], v13, v26
	s_and_b64 s[22:23], s[28:29], s[22:23]
	s_or_b64 s[0:1], s[0:1], s[22:23]
	v_cmp_eq_f32_e64 s[22:23], v10, v26
	v_cndmask_b32_e64 v30, 0, 1, s[0:1]
	v_cmp_lt_f32_e64 s[0:1], v10, v26
	s_and_b64 s[22:23], s[34:35], s[22:23]
	s_or_b64 s[0:1], s[0:1], s[22:23]
	v_cndmask_b32_e64 v31, 0, 1, s[0:1]
	s_movk_i32 s0, 0xffef
	v_cmp_eq_f32_e64 s[26:27], v11, v26
	v_cmp_lt_i32_e64 s[0:1], s0, v32
	v_cmp_lt_f32_e64 s[22:23], v11, v26
	s_and_b64 s[26:27], s[0:1], s[26:27]
	s_movk_i32 s30, 0xffeb
	s_or_b64 s[22:23], s[22:23], s[26:27]
	v_cmp_eq_f32_e64 s[26:27], v16, v26
	v_cmp_lt_i32_e64 s[30:31], s30, v32
	ds_bpermute_b32 v40, v17, v15 offset:192
	v_cndmask_b32_e64 v38, 0, 1, s[22:23]
	v_cmp_lt_f32_e64 s[22:23], v16, v26
	s_and_b64 s[26:27], s[30:31], s[26:27]
	s_movk_i32 s36, 0xffe7
	s_or_b64 s[22:23], s[22:23], s[26:27]
	v_cmp_eq_f32_e64 s[26:27], v9, v26
	v_cmp_lt_i32_e64 s[36:37], s36, v32
	v_cndmask_b32_e64 v39, 0, 1, s[22:23]
	v_cmp_lt_f32_e64 s[22:23], v9, v26
	s_and_b64 s[26:27], s[36:37], s[26:27]
	s_or_b64 s[22:23], s[22:23], s[26:27]
	v_cndmask_b32_e64 v26, 0, 1, s[22:23]
	s_waitcnt lgkmcnt(0)
	v_cmp_eq_f32_e64 s[36:37], v14, v40
	v_cmp_lt_i32_e64 s[22:23], 7, v32
	v_cmp_lt_f32_e64 s[26:27], v14, v40
	s_and_b64 s[36:37], s[22:23], s[36:37]
	s_or_b64 s[26:27], s[26:27], s[36:37]
	v_addc_co_u32_e64 v19, s[26:27], v19, v27, s[26:27]
	v_cmp_eq_f32_e64 s[36:37], v15, v40
	v_cmp_lt_f32_e64 s[26:27], v15, v40
	s_and_b64 s[36:37], s[18:19], s[36:37]
	s_or_b64 s[26:27], s[26:27], s[36:37]
	v_addc_co_u32_e64 v20, s[26:27], v20, v28, s[26:27]
	v_cmp_eq_f32_e64 s[36:37], v12, v40
	v_cmp_lt_f32_e64 s[26:27], v12, v40
	s_and_b64 s[36:37], s[20:21], s[36:37]
	s_or_b64 s[26:27], s[26:27], s[36:37]
	v_addc_co_u32_e64 v21, s[26:27], v21, v29, s[26:27]
	v_cmp_eq_f32_e64 s[36:37], v13, v40
	v_cmp_lt_f32_e64 s[26:27], v13, v40
	s_and_b64 s[36:37], s[24:25], s[36:37]
	s_or_b64 s[26:27], s[26:27], s[36:37]
	v_addc_co_u32_e64 v22, s[26:27], v22, v30, s[26:27]
	v_cmp_eq_f32_e64 s[36:37], v10, v40
	v_cmp_lt_f32_e64 s[26:27], v10, v40
	s_and_b64 s[36:37], s[28:29], s[36:37]
	s_or_b64 s[26:27], s[26:27], s[36:37]
	v_addc_co_u32_e64 v23, s[26:27], v23, v31, s[26:27]
	v_cmp_eq_f32_e64 s[36:37], v11, v40
	v_cmp_lt_f32_e64 s[26:27], v11, v40
	s_and_b64 s[36:37], s[34:35], s[36:37]
	s_or_b64 s[26:27], s[26:27], s[36:37]
	v_addc_co_u32_e64 v24, s[26:27], v24, v38, s[26:27]
	v_cmp_eq_f32_e64 s[36:37], v16, v40
	v_cmp_lt_f32_e64 s[26:27], v16, v40
	s_and_b64 s[36:37], s[0:1], s[36:37]
	s_or_b64 s[26:27], s[26:27], s[36:37]
	v_addc_co_u32_e64 v25, s[26:27], v25, v39, s[26:27]
	v_cmp_eq_f32_e64 s[36:37], v9, v40
	v_cmp_lt_f32_e64 s[26:27], v9, v40
	s_and_b64 s[30:31], s[30:31], s[36:37]
	s_or_b64 s[26:27], s[26:27], s[30:31]
	v_addc_co_u32_e64 v18, s[26:27], v18, v26, s[26:27]
	ds_bpermute_b32 v26, v17, v12 offset:192
	v_cmp_lt_i32_e64 s[26:27], 11, v32
	ds_bpermute_b32 v40, v17, v13 offset:192
	s_waitcnt lgkmcnt(1)
	v_cmp_eq_f32_e64 s[36:37], v14, v26
	v_cmp_lt_f32_e64 s[30:31], v14, v26
	s_and_b64 s[36:37], s[26:27], s[36:37]
	s_or_b64 s[30:31], s[30:31], s[36:37]
	v_cmp_eq_f32_e64 s[36:37], v15, v26
	v_cndmask_b32_e64 v27, 0, 1, s[30:31]
	v_cmp_lt_f32_e64 s[30:31], v15, v26
	s_and_b64 s[36:37], s[22:23], s[36:37]
	s_or_b64 s[30:31], s[30:31], s[36:37]
	v_cmp_eq_f32_e64 s[36:37], v12, v26
	v_cndmask_b32_e64 v28, 0, 1, s[30:31]
	v_cmp_lt_f32_e64 s[30:31], v12, v26
	s_and_b64 s[36:37], s[18:19], s[36:37]
	s_or_b64 s[30:31], s[30:31], s[36:37]
	v_cmp_eq_f32_e64 s[36:37], v13, v26
	v_cndmask_b32_e64 v29, 0, 1, s[30:31]
	v_cmp_lt_f32_e64 s[30:31], v13, v26
	s_and_b64 s[36:37], s[20:21], s[36:37]
	s_or_b64 s[30:31], s[30:31], s[36:37]
	v_cmp_eq_f32_e64 s[36:37], v10, v26
	v_cndmask_b32_e64 v30, 0, 1, s[30:31]
	v_cmp_lt_f32_e64 s[30:31], v10, v26
	s_and_b64 s[36:37], s[24:25], s[36:37]
	s_or_b64 s[30:31], s[30:31], s[36:37]
	v_cmp_eq_f32_e64 s[36:37], v11, v26
	v_cndmask_b32_e64 v31, 0, 1, s[30:31]
	v_cmp_lt_f32_e64 s[30:31], v11, v26
	s_and_b64 s[36:37], s[28:29], s[36:37]
	s_or_b64 s[30:31], s[30:31], s[36:37]
	v_cmp_eq_f32_e64 s[36:37], v16, v26
	v_cndmask_b32_e64 v38, 0, 1, s[30:31]
	v_cmp_lt_f32_e64 s[30:31], v16, v26
	s_and_b64 s[36:37], s[34:35], s[36:37]
	s_or_b64 s[30:31], s[30:31], s[36:37]
	v_cmp_eq_f32_e64 s[36:37], v9, v26
	v_cndmask_b32_e64 v39, 0, 1, s[30:31]
	v_cmp_lt_f32_e64 s[30:31], v9, v26
	s_and_b64 s[0:1], s[0:1], s[36:37]
	s_or_b64 s[0:1], s[30:31], s[0:1]
	s_waitcnt lgkmcnt(0)
	v_cmp_eq_f32_e64 s[36:37], v14, v40
	v_cmp_lt_i32_e64 s[30:31], 15, v32
	v_cndmask_b32_e64 v26, 0, 1, s[0:1]
	v_cmp_lt_f32_e64 s[0:1], v14, v40
	s_and_b64 s[36:37], s[30:31], s[36:37]
	s_or_b64 s[0:1], s[0:1], s[36:37]
	v_addc_co_u32_e64 v19, s[0:1], v19, v27, s[0:1]
	v_cmp_eq_f32_e64 s[36:37], v15, v40
	v_cmp_lt_f32_e64 s[0:1], v15, v40
	s_and_b64 s[36:37], s[26:27], s[36:37]
	s_or_b64 s[0:1], s[0:1], s[36:37]
	v_addc_co_u32_e64 v20, s[0:1], v20, v28, s[0:1]
	v_cmp_eq_f32_e64 s[36:37], v12, v40
	v_cmp_lt_f32_e64 s[0:1], v12, v40
	s_and_b64 s[36:37], s[22:23], s[36:37]
	s_or_b64 s[0:1], s[0:1], s[36:37]
	v_addc_co_u32_e64 v21, s[0:1], v21, v29, s[0:1]
	v_cmp_eq_f32_e64 s[36:37], v13, v40
	v_cmp_lt_f32_e64 s[0:1], v13, v40
	s_and_b64 s[36:37], s[18:19], s[36:37]
	s_or_b64 s[0:1], s[0:1], s[36:37]
	v_addc_co_u32_e64 v22, s[0:1], v22, v30, s[0:1]
	v_cmp_eq_f32_e64 s[36:37], v10, v40
	v_cmp_lt_f32_e64 s[0:1], v10, v40
	s_and_b64 s[36:37], s[20:21], s[36:37]
	s_or_b64 s[0:1], s[0:1], s[36:37]
	v_addc_co_u32_e64 v23, s[0:1], v23, v31, s[0:1]
	v_cmp_eq_f32_e64 s[36:37], v11, v40
	v_cmp_lt_f32_e64 s[0:1], v11, v40
	s_and_b64 s[36:37], s[24:25], s[36:37]
	s_or_b64 s[0:1], s[0:1], s[36:37]
	v_addc_co_u32_e64 v24, s[0:1], v24, v38, s[0:1]
	v_cmp_eq_f32_e64 s[36:37], v16, v40
	v_cmp_lt_f32_e64 s[0:1], v16, v40
	s_and_b64 s[36:37], s[28:29], s[36:37]
	s_or_b64 s[0:1], s[0:1], s[36:37]
	v_addc_co_u32_e64 v25, s[0:1], v25, v39, s[0:1]
	v_cmp_eq_f32_e64 s[36:37], v9, v40
	v_cmp_lt_f32_e64 s[0:1], v9, v40
	s_and_b64 s[34:35], s[34:35], s[36:37]
	s_or_b64 s[0:1], s[0:1], s[34:35]
	v_addc_co_u32_e64 v18, s[0:1], v18, v26, s[0:1]
	ds_bpermute_b32 v26, v17, v10 offset:192
	v_cmp_lt_i32_e64 s[34:35], 19, v32
	ds_bpermute_b32 v40, v17, v11 offset:192
	s_waitcnt lgkmcnt(1)
	v_cmp_eq_f32_e64 s[36:37], v14, v26
	v_cmp_lt_f32_e64 s[0:1], v14, v26
	s_and_b64 s[36:37], s[34:35], s[36:37]
	s_or_b64 s[0:1], s[0:1], s[36:37]
	v_cmp_eq_f32_e64 s[36:37], v15, v26
	v_cndmask_b32_e64 v27, 0, 1, s[0:1]
	v_cmp_lt_f32_e64 s[0:1], v15, v26
	s_and_b64 s[36:37], s[30:31], s[36:37]
	s_or_b64 s[0:1], s[0:1], s[36:37]
	v_cmp_eq_f32_e64 s[36:37], v12, v26
	v_cndmask_b32_e64 v28, 0, 1, s[0:1]
	v_cmp_lt_f32_e64 s[0:1], v12, v26
	s_and_b64 s[36:37], s[26:27], s[36:37]
	s_or_b64 s[0:1], s[0:1], s[36:37]
	v_cmp_eq_f32_e64 s[36:37], v13, v26
	v_cndmask_b32_e64 v29, 0, 1, s[0:1]
	v_cmp_lt_f32_e64 s[0:1], v13, v26
	s_and_b64 s[36:37], s[22:23], s[36:37]
	s_or_b64 s[0:1], s[0:1], s[36:37]
	v_cmp_eq_f32_e64 s[36:37], v10, v26
	v_cndmask_b32_e64 v30, 0, 1, s[0:1]
	v_cmp_lt_f32_e64 s[0:1], v10, v26
	s_and_b64 s[36:37], s[18:19], s[36:37]
	s_or_b64 s[0:1], s[0:1], s[36:37]
	v_cmp_eq_f32_e64 s[36:37], v11, v26
	v_cndmask_b32_e64 v31, 0, 1, s[0:1]
	v_cmp_lt_f32_e64 s[0:1], v11, v26
	s_and_b64 s[36:37], s[20:21], s[36:37]
	s_or_b64 s[0:1], s[0:1], s[36:37]
	v_cmp_eq_f32_e64 s[36:37], v16, v26
	v_cndmask_b32_e64 v38, 0, 1, s[0:1]
	v_cmp_lt_f32_e64 s[0:1], v16, v26
	s_and_b64 s[36:37], s[24:25], s[36:37]
	s_or_b64 s[0:1], s[0:1], s[36:37]
	v_cmp_eq_f32_e64 s[36:37], v9, v26
	v_cndmask_b32_e64 v39, 0, 1, s[0:1]
	v_cmp_lt_f32_e64 s[0:1], v9, v26
	s_and_b64 s[28:29], s[28:29], s[36:37]
	s_or_b64 s[0:1], s[0:1], s[28:29]
	v_cndmask_b32_e64 v26, 0, 1, s[0:1]
	s_waitcnt lgkmcnt(0)
	v_cmp_eq_f32_e64 s[36:37], v14, v40
	v_cmp_lt_i32_e64 s[0:1], 23, v32
	v_cmp_lt_f32_e64 s[28:29], v14, v40
	s_and_b64 s[36:37], s[0:1], s[36:37]
	s_or_b64 s[28:29], s[28:29], s[36:37]
	v_addc_co_u32_e64 v19, s[28:29], v19, v27, s[28:29]
	v_cmp_eq_f32_e64 s[36:37], v15, v40
	v_cmp_lt_f32_e64 s[28:29], v15, v40
	s_and_b64 s[36:37], s[34:35], s[36:37]
	s_or_b64 s[28:29], s[28:29], s[36:37]
	v_addc_co_u32_e64 v20, s[28:29], v20, v28, s[28:29]
	v_cmp_eq_f32_e64 s[36:37], v12, v40
	v_cmp_lt_f32_e64 s[28:29], v12, v40
	s_and_b64 s[36:37], s[30:31], s[36:37]
	s_or_b64 s[28:29], s[28:29], s[36:37]
	v_addc_co_u32_e64 v21, s[28:29], v21, v29, s[28:29]
	v_cmp_eq_f32_e64 s[36:37], v13, v40
	v_cmp_lt_f32_e64 s[28:29], v13, v40
	s_and_b64 s[36:37], s[26:27], s[36:37]
	s_or_b64 s[28:29], s[28:29], s[36:37]
	v_addc_co_u32_e64 v22, s[28:29], v22, v30, s[28:29]
	v_cmp_eq_f32_e64 s[36:37], v10, v40
	v_cmp_lt_f32_e64 s[28:29], v10, v40
	s_and_b64 s[36:37], s[22:23], s[36:37]
	s_or_b64 s[28:29], s[28:29], s[36:37]
	v_addc_co_u32_e64 v23, s[28:29], v23, v31, s[28:29]
	v_cmp_eq_f32_e64 s[36:37], v11, v40
	v_cmp_lt_f32_e64 s[28:29], v11, v40
	s_and_b64 s[36:37], s[18:19], s[36:37]
	s_or_b64 s[28:29], s[28:29], s[36:37]
	v_addc_co_u32_e64 v24, s[28:29], v24, v38, s[28:29]
	v_cmp_eq_f32_e64 s[36:37], v16, v40
	v_cmp_lt_f32_e64 s[28:29], v16, v40
	s_and_b64 s[36:37], s[20:21], s[36:37]
	s_or_b64 s[28:29], s[28:29], s[36:37]
	v_addc_co_u32_e64 v25, s[28:29], v25, v39, s[28:29]
	v_cmp_eq_f32_e64 s[36:37], v9, v40
	v_cmp_lt_f32_e64 s[28:29], v9, v40
	s_and_b64 s[24:25], s[24:25], s[36:37]
	s_or_b64 s[24:25], s[28:29], s[24:25]
	v_addc_co_u32_e64 v18, s[24:25], v18, v26, s[24:25]
	ds_bpermute_b32 v26, v17, v16 offset:192
	v_cmp_lt_i32_e64 s[36:37], 27, v32
	ds_bpermute_b32 v17, v17, v9 offset:192
	s_waitcnt lgkmcnt(1)
	v_cmp_eq_f32_e64 s[28:29], v14, v26
	v_cmp_lt_f32_e64 s[24:25], v14, v26
	s_and_b64 s[28:29], s[36:37], s[28:29]
	s_or_b64 s[24:25], s[24:25], s[28:29]
	v_cmp_eq_f32_e64 s[28:29], v15, v26
	v_cndmask_b32_e64 v27, 0, 1, s[24:25]
	v_cmp_lt_f32_e64 s[24:25], v15, v26
	s_and_b64 s[28:29], s[0:1], s[28:29]
	s_or_b64 s[24:25], s[24:25], s[28:29]
	v_cmp_eq_f32_e64 s[28:29], v12, v26
	v_cndmask_b32_e64 v28, 0, 1, s[24:25]
	v_cmp_lt_f32_e64 s[24:25], v12, v26
	s_and_b64 s[28:29], s[34:35], s[28:29]
	s_or_b64 s[24:25], s[24:25], s[28:29]
	v_cmp_eq_f32_e64 s[28:29], v13, v26
	v_cndmask_b32_e64 v29, 0, 1, s[24:25]
	v_cmp_lt_f32_e64 s[24:25], v13, v26
	s_and_b64 s[28:29], s[30:31], s[28:29]
	s_or_b64 s[24:25], s[24:25], s[28:29]
	v_cmp_eq_f32_e64 s[28:29], v10, v26
	v_cndmask_b32_e64 v30, 0, 1, s[24:25]
	v_cmp_lt_f32_e64 s[24:25], v10, v26
	s_and_b64 s[28:29], s[26:27], s[28:29]
	s_or_b64 s[24:25], s[24:25], s[28:29]
	v_cmp_eq_f32_e64 s[28:29], v11, v26
	v_cndmask_b32_e64 v31, 0, 1, s[24:25]
	v_cmp_lt_f32_e64 s[24:25], v11, v26
	s_and_b64 s[28:29], s[22:23], s[28:29]
	s_or_b64 s[24:25], s[24:25], s[28:29]
	v_cmp_eq_f32_e64 s[28:29], v16, v26
	v_cndmask_b32_e64 v38, 0, 1, s[24:25]
	v_cmp_lt_f32_e64 s[24:25], v16, v26
	s_and_b64 s[28:29], s[18:19], s[28:29]
	s_or_b64 s[24:25], s[24:25], s[28:29]
	v_cmp_eq_f32_e64 s[28:29], v9, v26
	v_cndmask_b32_e64 v39, 0, 1, s[24:25]
	v_cmp_lt_f32_e64 s[24:25], v9, v26
	s_and_b64 s[20:21], s[20:21], s[28:29]
	s_or_b64 s[20:21], s[24:25], s[20:21]
	s_waitcnt lgkmcnt(0)
	v_cmp_eq_f32_e64 s[24:25], v14, v17
	v_cmp_lt_i32_e64 s[28:29], 31, v32
	v_cndmask_b32_e64 v26, 0, 1, s[20:21]
	v_cmp_lt_f32_e64 s[20:21], v14, v17
	s_and_b64 s[24:25], s[28:29], s[24:25]
	s_or_b64 s[20:21], s[20:21], s[24:25]
	v_addc_co_u32_e64 v14, s[20:21], v19, v27, s[20:21]
	v_cmp_eq_f32_e64 s[24:25], v15, v17
	v_cmp_lt_f32_e64 s[20:21], v15, v17
	s_and_b64 s[24:25], s[36:37], s[24:25]
	s_or_b64 s[20:21], s[20:21], s[24:25]
	v_addc_co_u32_e64 v15, s[20:21], v20, v28, s[20:21]
	v_cmp_eq_f32_e64 s[24:25], v12, v17
	v_cmp_lt_f32_e64 s[20:21], v12, v17
	s_and_b64 s[0:1], s[0:1], s[24:25]
	s_or_b64 s[0:1], s[20:21], s[0:1]
	v_addc_co_u32_e64 v12, s[0:1], v21, v29, s[0:1]
	v_cmp_eq_f32_e64 s[20:21], v13, v17
	v_cmp_lt_f32_e64 s[0:1], v13, v17
	s_and_b64 s[20:21], s[34:35], s[20:21]
	s_or_b64 s[0:1], s[0:1], s[20:21]
	v_addc_co_u32_e64 v13, s[0:1], v22, v30, s[0:1]
	v_cmp_eq_f32_e64 s[20:21], v10, v17
	v_cmp_lt_f32_e64 s[0:1], v10, v17
	s_and_b64 s[20:21], s[30:31], s[20:21]
	s_or_b64 s[0:1], s[0:1], s[20:21]
	v_addc_co_u32_e64 v10, s[0:1], v23, v31, s[0:1]
	v_cmp_eq_f32_e64 s[20:21], v11, v17
	v_cmp_lt_f32_e64 s[0:1], v11, v17
	s_and_b64 s[20:21], s[26:27], s[20:21]
	s_or_b64 s[0:1], s[0:1], s[20:21]
	v_addc_co_u32_e64 v11, s[0:1], v24, v38, s[0:1]
	v_cmp_eq_f32_e64 s[20:21], v16, v17
	v_cmp_lt_f32_e64 s[0:1], v16, v17
	s_and_b64 s[20:21], s[22:23], s[20:21]
	s_or_b64 s[0:1], s[0:1], s[20:21]
	v_addc_co_u32_e64 v16, s[0:1], v25, v39, s[0:1]
	v_cmp_eq_f32_e64 s[20:21], v9, v17
	v_cmp_lt_f32_e64 s[0:1], v9, v17
	s_and_b64 s[18:19], s[18:19], s[20:21]
	s_or_b64 s[0:1], s[0:1], s[18:19]
	v_addc_co_u32_e64 v9, s[0:1], v18, v26, s[0:1]
	v_cmp_lt_u32_e64 s[0:1], 7, v14
	s_or_b64 s[0:1], vcc, s[0:1]
	v_lshlrev_b32_e64 v14, v32, 1
	v_cmp_lt_u32_e32 vcc, 7, v15
	v_cndmask_b32_e64 v14, v14, 0, s[0:1]
	s_or_b64 s[0:1], s[4:5], vcc
	v_cmp_lt_u32_e32 vcc, 7, v12
	v_cndmask_b32_e64 v2, v2, 0, s[0:1]
	s_or_b64 s[0:1], s[6:7], vcc
	v_cmp_lt_u32_e32 vcc, 7, v13
	v_cndmask_b32_e64 v3, v3, 0, s[0:1]
	s_or_b64 s[0:1], s[8:9], vcc
	v_or_b32_e32 v2, v2, v14
	v_cndmask_b32_e64 v4, v4, 0, s[0:1]
	v_cmp_lt_u32_e32 vcc, 7, v10
	v_or3_b32 v2, v2, v3, v4
	s_or_b64 s[0:1], s[10:11], vcc
	v_lshlrev_b32_e64 v3, v5, 1
	v_cmp_lt_u32_e32 vcc, 7, v11
	v_cndmask_b32_e64 v3, v3, 0, s[0:1]
	s_or_b64 s[0:1], s[12:13], vcc
	v_lshlrev_b32_e64 v4, v6, 1
	v_cndmask_b32_e64 v4, v4, 0, s[0:1]
	v_cmp_lt_u32_e32 vcc, 7, v16
	v_or3_b32 v2, v2, v3, v4
	s_or_b64 s[0:1], s[14:15], vcc
	v_lshlrev_b32_e64 v3, v7, 1
	v_cmp_lt_u32_e32 vcc, 7, v9
	v_cndmask_b32_e64 v3, v3, 0, s[0:1]
	s_or_b64 s[0:1], s[16:17], vcc
	v_lshlrev_b32_e64 v4, v8, 1
	v_cndmask_b32_e64 v4, v4, 0, s[0:1]
	v_or3_b32 v2, v2, v3, v4
	ds_bpermute_b32 v3, v193, v2
	v_cmp_lt_i32_e32 vcc, v214, v213
	s_waitcnt lgkmcnt(0)
	v_or_b32_e32 v2, v2, v3
	ds_bpermute_b32 v3, v194, v2
	s_waitcnt lgkmcnt(0)
	v_or_b32_e32 v195, v2, v3
	v_cndmask_b32_e32 v2, v211, v214, vcc
	v_lshlrev_b32_e32 v2, 2, v2
	ds_bpermute_b32 v2, v2, v195
	v_cmp_lt_i32_e32 vcc, v215, v213
	s_waitcnt lgkmcnt(0)
	v_or_b32_e32 v2, v195, v2
	v_cndmask_b32_e32 v3, v211, v215, vcc
	v_lshlrev_b32_e32 v3, 2, v3
	ds_bpermute_b32 v3, v3, v2
	v_cmp_lt_i32_e32 vcc, v216, v213
	s_waitcnt lgkmcnt(0)
	v_or_b32_e32 v2, v2, v3
	v_cndmask_b32_e32 v3, v211, v216, vcc
	v_lshlrev_b32_e32 v3, 2, v3
	ds_bpermute_b32 v3, v3, v2
	v_cmp_lt_i32_e32 vcc, v217, v213
	s_waitcnt lgkmcnt(0)
	v_or_b32_e32 v2, v2, v3
	v_cndmask_b32_e32 v3, v211, v217, vcc
	v_lshlrev_b32_e32 v3, 2, v3
	ds_bpermute_b32 v3, v3, v2
	s_waitcnt lgkmcnt(0)
	v_or_b32_e32 v40, v2, v3
	s_add_u32 s16, s86, 0x29200000
	v_lshl_add_u64 v[0:1], v[146:147], 1, v[0:1]
	s_mov_b64 s[0:1], 0x15200000
	s_addc_u32 s17, s87, 0
	v_lshl_add_u64 v[38:39], v[0:1], 0, s[0:1]
	s_lshl_b32 s82, s2, 9
	v_lshl_add_u64 v[28:29], v[38:39], 0, s[82:83]
	global_load_dwordx4 v[0:3], v[28:29], off
	global_load_dwordx4 v[4:7], v[28:29], off offset:64
	global_load_dwordx4 v[8:11], v[28:29], off offset:128
	global_load_dwordx4 v[12:15], v[28:29], off offset:192
	global_load_dwordx4 v[16:19], v[28:29], off offset:256
	global_load_dwordx4 v[20:23], v[28:29], off offset:320
	global_load_dwordx4 v[24:27], v[28:29], off offset:384
	s_nop 0
	global_load_dwordx4 v[28:31], v[28:29], off offset:448
	v_lshlrev_b64 v[32:33], 3, v[32:33]
	v_sub_co_u32_e32 v32, vcc, 0, v32
	v_mul_f32_e32 v196, 0x3fb8aa3b, v34
	v_readfirstlane_b32 s18, v40
	v_subb_co_u32_e32 v33, vcc, 0, v33, vcc
	v_mov_b32_e32 v34, 0x1ff
	s_ff1_i32_b32 s0, s18
	v_sub_co_u32_e32 v34, vcc, s81, v34
	s_ashr_i32 s95, s94, 31
	s_lshl_b32 s19, s0, 6
	v_readfirstlane_b32 s0, v34
	s_lshl_b64 s[6:7], s[94:95], 19
	s_lshl_b32 s4, s2, 6
	s_lshl_b64 s[8:9], s[84:85], 18
	s_sub_i32 s2, s81, 17
	s_add_i32 s20, s18, -1
	s_and_b32 s5, s0, 0xffffffe0
	v_lshl_add_u64 v[32:33], v[38:39], 0, v[32:33]
	s_and_b64 s[0:1], vcc, exec
	v_lshlrev_b32_e32 v34, 11, v190
	v_mul_f32_e32 v197, 0x3fb8aa3b, v35
	v_mul_f32_e32 v198, 0x3fb8aa3b, v36
	v_mul_f32_e32 v199, 0x3fb8aa3b, v37
	s_cselect_b32 s21, 0, s5
	v_add_u32_e32 v200, 0xfffffe01, v191
	v_lshl_add_u64 v[150:151], v[32:33], 0, s[82:83]
	s_mov_b64 s[10:11], 0
	s_lshl_b32 s22, s4, 1
	v_lshlrev_b32_e32 v152, 1, v34
	v_readlane_b32 s56, v252, 21
	v_readlane_b32 s57, v252, 22
	v_lshrrev_b32_e32 v251, 2, v190
	v_and_b32_e32 v250, 3, v190
	v_lshl_or_b32 v251, v251, 3, v250
	s_branch .LBB0_191

.LBB0_191:
	s_xor_b64 s[12:13], s[10:11], -1
	s_and_b64 s[0:1], s[10:11], exec
	s_cselect_b32 s82, s21, s19
	s_cmp_lt_i32 s82, 0
	s_cbranch_scc1 .LBB0_202
	s_lshl_b32 s0, s38, 25
	s_add_u32 s4, s16, s0
	s_addc_u32 s5, s17, 0
	s_add_u32 s0, s4, s6
	s_addc_u32 s1, s5, s7
	s_add_u32 s0, s0, s22
	v_or_b32_e32 v32, s82, v251
	s_addc_u32 s1, s1, 0
	v_or_b32_e32 v160, 4, v32
	v_mov_b32_e32 v33, v161
	v_lshl_add_u64 v[158:159], v[146:147], 1, s[0:1]
	v_lshlrev_b64 v[34:35], 8, v[160:161]
	v_lshlrev_b64 v[32:33], 8, v[32:33]
	v_lshl_add_u64 v[34:35], v[158:159], 0, v[34:35]
	v_lshl_add_u64 v[32:33], v[158:159], 0, v[32:33]
	global_load_dwordx4 v[96:99], v[34:35], off offset:64
	global_load_dwordx4 v[100:103], v[34:35], off
	global_load_dwordx4 v[104:107], v[32:33], off offset:64
	global_load_dwordx4 v[108:111], v[32:33], off
	s_add_u32 s0, s4, s8
	s_addc_u32 s1, s5, s9
	v_lshl_add_u64 v[32:33], v[144:145], 2, s[0:1]
	v_mov_b32_e32 v153, v161
	s_and_b64 s[4:5], s[10:11], exec
	v_lshl_add_u64 v[32:33], v[32:33], 0, v[152:153]
	s_mov_b64 s[0:1], 0x1000000
	s_cselect_b32 s4, -1, s20
	v_cndmask_b32_e64 v160, 0, v200, s[10:11]
	v_lshl_add_u64 v[170:171], v[32:33], 0, s[0:1]
	v_mov_b32_e32 v32, 0
	s_and_b32 s4, s4, s18
	v_add_u32_e32 v153, -1, v160
	v_mov_b32_e32 v172, 0xf149f2ca
	v_mov_b32_e32 v177, 0xf149f2ca
	v_mov_b32_e32 v175, 0xf149f2ca
	v_mov_b32_e32 v173, 0xf149f2ca
	v_mov_b32_e32 v33, v32
	v_mov_b32_e32 v34, v32
	v_mov_b32_e32 v35, v32
	v_mov_b32_e32 v36, v32
	v_mov_b32_e32 v37, v32
	v_mov_b32_e32 v38, v32
	v_mov_b32_e32 v39, v32
	v_mov_b32_e32 v40, v32
	v_mov_b32_e32 v41, v32
	v_mov_b32_e32 v42, v32
	v_mov_b32_e32 v43, v32
	v_mov_b32_e32 v44, v32
	v_mov_b32_e32 v45, v32
	v_mov_b32_e32 v46, v32
	v_mov_b32_e32 v47, v32
	v_mov_b32_e32 v48, v32
	v_mov_b32_e32 v49, v32
	v_mov_b32_e32 v50, v32
	v_mov_b32_e32 v51, v32
	v_mov_b32_e32 v52, v32
	v_mov_b32_e32 v53, v32
	v_mov_b32_e32 v54, v32
	v_mov_b32_e32 v55, v32
	v_mov_b32_e32 v56, v32
	v_mov_b32_e32 v57, v32
	v_mov_b32_e32 v58, v32
	v_mov_b32_e32 v59, v32
	v_mov_b32_e32 v60, v32
	v_mov_b32_e32 v61, v32
	v_mov_b32_e32 v62, v32
	v_mov_b32_e32 v63, v32
	v_mov_b32_e32 v64, v32
	v_mov_b32_e32 v65, v32
	v_mov_b32_e32 v66, v32
	v_mov_b32_e32 v67, v32
	v_mov_b32_e32 v68, v32
	v_mov_b32_e32 v69, v32
	v_mov_b32_e32 v70, v32
	v_mov_b32_e32 v71, v32
	v_mov_b32_e32 v72, v32
	v_mov_b32_e32 v73, v32
	v_mov_b32_e32 v74, v32
	v_mov_b32_e32 v75, v32
	v_mov_b32_e32 v76, v32
	v_mov_b32_e32 v77, v32
	v_mov_b32_e32 v78, v32
	v_mov_b32_e32 v79, v32
	v_mov_b32_e32 v80, v32
	v_mov_b32_e32 v81, v32
	v_mov_b32_e32 v82, v32
	v_mov_b32_e32 v83, v32
	v_mov_b32_e32 v84, v32
	v_mov_b32_e32 v85, v32
	v_mov_b32_e32 v86, v32
	v_mov_b32_e32 v87, v32
	v_mov_b32_e32 v88, v32
	v_mov_b32_e32 v89, v32
	v_mov_b32_e32 v90, v32
	v_mov_b32_e32 v91, v32
	v_mov_b32_e32 v92, v32
	v_mov_b32_e32 v93, v32
	v_mov_b32_e32 v94, v32
	v_mov_b32_e32 v95, v32
	v_mov_b32_e32 v156, v32
	v_mov_b32_e32 v157, v32
	v_mov_b32_e32 v154, v32
	v_mov_b32_e32 v155, v32
	s_andn2_b64 vcc, exec, s[12:13]
	s_mov_b64 s[0:1], -1
	s_cbranch_vccnz .LBB0_198

.LBB0_200:
	s_lshr_b32 s0, s82, 6
	s_lshl_b32 s0, 1, s0
	v_and_b32_e32 v112, s0, v195
	v_cmp_ne_u32_e32 vcc, 0, v112
	s_or_b64 s[14:15], s[10:11], vcc
	s_cmp_lt_i32 s23, 0
	s_cselect_b64 s[4:5], -1, 0
	s_and_b64 s[0:1], s[4:5], exec
	s_cselect_b32 s0, s82, s23
	v_add_u32_e32 v120, s0, v251
	v_ashrrev_i32_e32 v121, 31, v120
	v_lshlrev_b64 v[112:113], 8, v[120:121]
	v_add_u32_e32 v120, 4, v120
	v_ashrrev_i32_e32 v121, 31, v120
	v_lshl_add_u64 v[128:129], s[82:83], 1, v[170:171]
	v_lshlrev_b64 v[120:121], 8, v[120:121]
	v_add_co_u32_e32 v130, vcc, s3, v128
	v_lshl_add_u64 v[116:117], v[158:159], 0, v[112:113]
	v_lshl_add_u64 v[124:125], v[158:159], 0, v[120:121]
	v_addc_co_u32_e32 v131, vcc, 0, v129, vcc
	s_mov_b32 s0, 0x20000
	global_load_dwordx4 v[136:139], v[128:129], off
	s_nop 0
	global_load_dwordx4 v[140:143], v[130:131], off
	s_nop 0
	v_add_co_u32_e32 v130, vcc, s0, v128
	s_mov_b32 s0, 0x30000
	s_nop 0
	v_addc_co_u32_e32 v131, vcc, 0, v129, vcc
	global_load_dwordx4 v[132:135], v[130:131], off
	s_nop 0
	v_add_co_u32_e32 v130, vcc, s0, v128
	v_lshl_add_u32 v166, v144, 1, s82
	s_nop 0
	v_addc_co_u32_e32 v131, vcc, 0, v129, vcc
	global_load_dwordx4 v[128:131], v[130:131], off
	s_nop 0
	s_nop 0
	global_load_dwordx4 v[112:115], v[116:117], off
	s_nop 0
	global_load_dwordx4 v[116:119], v[116:117], off offset:64
	s_nop 0
	global_load_dwordx4 v[120:123], v[124:125], off
	s_nop 0
	global_load_dwordx4 v[124:127], v[124:125], off offset:64
	v_cmp_ge_i32_e32 vcc, v166, v160
	v_cmp_lt_i32_e64 s[0:1], v191, v166
	v_add_u32_e32 v167, 4, v166
	s_and_b64 vcc, s[14:15], vcc
	v_cndmask_b32_e64 v168, 0, v223, s[0:1]
	v_cndmask_b32_e32 v179, v223, v168, vcc
	v_cmp_ge_i32_e32 vcc, v167, v160
	v_cmp_gt_i32_e64 s[0:1], v167, v191
	s_and_b64 vcc, s[14:15], vcc
	v_add_u32_e32 v168, 6, v166
	v_cndmask_b32_e64 v167, 0, v223, s[0:1]
	v_cndmask_b32_e32 v181, v223, v167, vcc
	v_cmp_ge_i32_e32 vcc, v166, v153
	v_cmp_gt_i32_e64 s[0:1], v191, v166
	s_and_b64 s[0:1], s[0:1], vcc
	v_add_u32_e32 v167, 5, v166
	s_and_b64 s[0:1], s[14:15], s[0:1]
	v_cndmask_b32_e64 v183, v223, 0, s[0:1]
	v_cmp_ge_i32_e32 vcc, v167, v160
	v_cmp_gt_i32_e64 s[0:1], v167, v191
	s_and_b64 vcc, s[14:15], vcc
	s_waitcnt vmcnt(8)
	v_mfma_f32_16x16x32_bf16 v[228:231], v[108:111], v[0:3], 0
	v_cndmask_b32_e64 v167, 0, v223, s[0:1]
	v_cndmask_b32_e32 v185, v223, v167, vcc
	v_add_u32_e32 v167, 2, v166
	v_cmp_ge_i32_e32 vcc, v167, v160
	v_cmp_gt_i32_e64 s[0:1], v167, v191
	s_and_b64 vcc, s[14:15], vcc
	v_mfma_f32_16x16x32_bf16 v[232:235], v[100:103], v[0:3], 0
	v_cndmask_b32_e64 v167, 0, v223, s[0:1]
	v_cndmask_b32_e32 v187, v223, v167, vcc
	v_cmp_ge_i32_e32 vcc, v168, v160
	v_cmp_gt_i32_e64 s[0:1], v168, v191
	s_and_b64 vcc, s[14:15], vcc
	v_add_u32_e32 v168, 7, v166
	v_cndmask_b32_e64 v167, 0, v223, s[0:1]
	v_cndmask_b32_e32 v189, v223, v167, vcc
	v_add_u32_e32 v167, 3, v166
	v_sub_u32_e32 v166, v191, v166
	v_cvt_f32_i32_e32 v204, v166
	v_cmp_ge_i32_e32 vcc, v167, v160
	v_cmp_gt_i32_e64 s[0:1], v167, v191
	s_and_b64 vcc, s[14:15], vcc
	v_mfma_f32_16x16x32_bf16 v[228:231], v[104:107], v[4:7], v[228:231]
	v_cndmask_b32_e64 v167, 0, v223, s[0:1]
	v_cndmask_b32_e32 v202, v223, v167, vcc
	v_cmp_ge_i32_e32 vcc, v168, v160
	v_mfma_f32_16x16x32_bf16 v[232:235], v[96:99], v[4:7], v[232:235]
	v_cmp_gt_i32_e64 s[0:1], v168, v191
	s_and_b64 vcc, s[14:15], vcc
	v_mul_f32_e64 v166, -v196, v204
	v_cndmask_b32_e64 v167, 0, v223, s[0:1]
	v_cndmask_b32_e32 v203, v223, v167, vcc
	v_fma_f32 v167, 0, v196, v166
	v_fmamk_f32 v168, v196, 0x40800000, v166
	v_fma_f32 v174, -v196, v204, v196
	v_fmamk_f32 v176, v196, 0x40a00000, v166
	v_fmac_f32_e32 v167, 0x3e38aa3b, v228
	v_fmac_f32_e32 v168, 0x3e38aa3b, v232
	v_fmac_f32_e32 v174, 0x3e38aa3b, v229
	v_fmac_f32_e32 v176, 0x3e38aa3b, v233
	v_add_f32_e32 v167, v179, v167
	v_add_f32_e32 v168, v181, v168
	v_add_f32_e32 v174, v183, v174
	v_add_f32_e32 v182, v185, v176
	v_max_f32_e32 v169, v167, v168
	v_max_f32_e32 v176, v174, v182
	v_max3_f32 v169, v169, s73, v176
	v_fma_f32 v176, 2.0, v196, v166
	v_fmamk_f32 v178, v196, 0x40c00000, v166
	v_fmamk_f32 v180, v196, 0x40400000, v166
	v_fmac_f32_e32 v166, 0x40e00000, v196
	v_fmac_f32_e32 v176, 0x3e38aa3b, v230
	v_fmac_f32_e32 v178, 0x3e38aa3b, v234
	v_fmac_f32_e32 v180, 0x3e38aa3b, v231
	v_fmac_f32_e32 v166, 0x3e38aa3b, v235
	v_add_f32_e32 v176, v187, v176
	v_add_f32_e32 v186, v189, v178
	v_add_f32_e32 v180, v202, v180
	v_add_f32_e32 v166, v203, v166
	v_max_f32_e32 v178, v176, v186
	v_max_f32_e32 v184, v180, v166
	v_max3_f32 v169, v169, v178, v184
	v_mov_b32_e32 v178, v169
	v_mfma_f32_16x16x32_bf16 v[232:235], v[100:103], v[8:11], 0
	v_fma_f32 v205, -v197, v204, v197
	v_permlane16_swap_b32_e32 v178, v169
	v_max_f32_e32 v169, v169, v178
	v_mov_b32_e32 v178, v169
	v_mfma_f32_16x16x32_bf16 v[232:235], v[96:99], v[12:15], v[232:235]
	s_nop 0
	v_permlane32_swap_b32_e32 v178, v169
	v_max3_f32 v201, v172, v169, v178
	v_sub_f32_e32 v167, v167, v201
	v_sub_f32_e32 v169, v172, v201
	v_exp_f32_e32 v172, v167
	v_sub_f32_e32 v167, v174, v201
	v_exp_f32_e32 v174, v167
	v_sub_f32_e32 v167, v176, v201
	v_exp_f32_e32 v176, v167
	v_sub_f32_e32 v167, v180, v201
	v_exp_f32_e32 v178, v167
	v_sub_f32_e32 v167, v168, v201
	v_exp_f32_e32 v180, v167
	v_sub_f32_e32 v167, v182, v201
	v_exp_f32_e32 v184, v167
	v_sub_f32_e32 v167, v186, v201
	v_sub_f32_e32 v166, v166, v201
	v_exp_f32_e32 v186, v167
	v_exp_f32_e32 v188, v166
	v_exp_f32_e32 v182, v169
	v_cvt_pk_bf16_f32 v228, v172, v174
	v_cvt_pk_bf16_f32 v229, v176, v178
	v_cvt_pk_bf16_f32 v230, v180, v184
	v_cvt_pk_bf16_f32 v231, v186, v188
	v_pk_mul_f32 v[94:95], v[94:95], v[182:183] op_sel_hi:[1,0]
	v_pk_mul_f32 v[92:93], v[92:93], v[182:183] op_sel_hi:[1,0]
	v_pk_mul_f32 v[90:91], v[90:91], v[182:183] op_sel_hi:[1,0]
	v_pk_mul_f32 v[88:89], v[88:89], v[182:183] op_sel_hi:[1,0]
	v_pk_mul_f32 v[86:87], v[86:87], v[182:183] op_sel_hi:[1,0]
	v_pk_mul_f32 v[84:85], v[84:85], v[182:183] op_sel_hi:[1,0]
	v_pk_mul_f32 v[82:83], v[82:83], v[182:183] op_sel_hi:[1,0]
	v_pk_mul_f32 v[80:81], v[80:81], v[182:183] op_sel_hi:[1,0]
	s_waitcnt vmcnt(4)
	v_mfma_f32_16x16x32_bf16 v[92:95], v[136:139], v[228:231], v[92:95]
	v_mul_f32_e64 v166, -v197, v204
	v_fma_f32 v167, 0, v197, v166
	v_fmamk_f32 v168, v197, 0x40800000, v166
	v_mfma_f32_16x16x32_bf16 v[88:91], v[140:143], v[228:231], v[88:91]
	v_fmac_f32_e32 v168, 0x3e38aa3b, v232
	v_add_f32_e32 v169, v181, v168
	v_mfma_f32_16x16x32_bf16 v[84:87], v[132:135], v[228:231], v[84:87]
	v_mfma_f32_16x16x32_bf16 v[80:83], v[128:131], v[228:231], v[80:83]
	v_mfma_f32_16x16x32_bf16 v[228:231], v[108:111], v[8:11], 0
	v_mfma_f32_16x16x32_bf16 v[228:231], v[104:107], v[12:15], v[228:231]
	s_nop 7
	v_fmac_f32_e32 v205, 0x3e38aa3b, v229
	v_add_f32_e32 v206, v183, v205
	v_fmamk_f32 v205, v197, 0x40a00000, v166
	v_fmac_f32_e32 v167, 0x3e38aa3b, v228
	v_fmac_f32_e32 v205, 0x3e38aa3b, v233
	v_add_f32_e32 v167, v179, v167
	v_add_f32_e32 v207, v185, v205
	v_max_f32_e32 v168, v167, v169
	v_max_f32_e32 v205, v206, v207
	v_max3_f32 v168, v168, s73, v205
	v_fma_f32 v205, 2.0, v197, v166
	v_fmac_f32_e32 v205, 0x3e38aa3b, v230
	v_add_f32_e32 v228, v187, v205
	v_fmamk_f32 v205, v197, 0x40c00000, v166
	v_fmamk_f32 v230, v197, 0x40400000, v166
	v_fmac_f32_e32 v166, 0x40e00000, v197
	v_fmac_f32_e32 v205, 0x3e38aa3b, v234
	v_fmac_f32_e32 v230, 0x3e38aa3b, v231
	v_fmac_f32_e32 v166, 0x3e38aa3b, v235
	v_add_f32_e32 v229, v189, v205
	v_add_f32_e32 v230, v202, v230
	v_add_f32_e32 v231, v203, v166
	v_max_f32_e32 v205, v228, v229
	v_max_f32_e32 v166, v230, v231
	v_max3_f32 v166, v168, v205, v166
	v_mov_b32_e32 v168, v166
	s_nop 1
	v_permlane16_swap_b32_e32 v168, v166
	v_max_f32_e32 v166, v166, v168
	v_mov_b32_e32 v168, v166
	s_nop 1
	v_permlane32_swap_b32_e32 v168, v166
	v_max3_f32 v205, v177, v166, v168
	v_sub_f32_e32 v166, v167, v205
	v_sub_f32_e32 v167, v206, v205
	v_exp_f32_e32 v168, v167
	v_sub_f32_e32 v167, v228, v205
	v_exp_f32_e32 v236, v167
	v_sub_f32_e32 v167, v230, v205
	v_exp_f32_e32 v238, v167
	v_sub_f32_e32 v167, v169, v205
	v_exp_f32_e32 v240, v167
	v_sub_f32_e32 v167, v207, v205
	v_exp_f32_e32 v242, v167
	v_sub_f32_e32 v167, v229, v205
	v_sub_f32_e32 v177, v177, v205
	v_exp_f32_e32 v244, v167
	v_sub_f32_e32 v167, v231, v205
	v_exp_f32_e32 v166, v166
	v_exp_f32_e32 v246, v167
	v_exp_f32_e32 v248, v177
	v_cvt_pk_bf16_f32 v229, v236, v238
	v_cvt_pk_bf16_f32 v228, v166, v168
	v_cvt_pk_bf16_f32 v230, v240, v242
	v_cvt_pk_bf16_f32 v231, v244, v246
	v_pk_mul_f32 v[78:79], v[78:79], v[248:249] op_sel_hi:[1,0]
	v_pk_mul_f32 v[76:77], v[76:77], v[248:249] op_sel_hi:[1,0]
	v_pk_mul_f32 v[74:75], v[74:75], v[248:249] op_sel_hi:[1,0]
	v_pk_mul_f32 v[72:73], v[72:73], v[248:249] op_sel_hi:[1,0]
	v_pk_mul_f32 v[70:71], v[70:71], v[248:249] op_sel_hi:[1,0]
	v_pk_mul_f32 v[68:69], v[68:69], v[248:249] op_sel_hi:[1,0]
	v_pk_mul_f32 v[66:67], v[66:67], v[248:249] op_sel_hi:[1,0]
	v_pk_mul_f32 v[64:65], v[64:65], v[248:249] op_sel_hi:[1,0]
	v_mfma_f32_16x16x32_bf16 v[76:79], v[136:139], v[228:231], v[76:79]
	v_mfma_f32_16x16x32_bf16 v[72:75], v[140:143], v[228:231], v[72:75]
	v_mfma_f32_16x16x32_bf16 v[68:71], v[132:135], v[228:231], v[68:71]
	v_mfma_f32_16x16x32_bf16 v[64:67], v[128:131], v[228:231], v[64:67]
	v_mfma_f32_16x16x32_bf16 v[228:231], v[108:111], v[16:19], 0
	v_mul_f32_e64 v167, -v198, v204
	v_fma_f32 v169, 0, v198, v167
	v_fmamk_f32 v177, v198, 0x40800000, v167
	v_mfma_f32_16x16x32_bf16 v[232:235], v[100:103], v[16:19], 0
	v_fma_f32 v207, -v198, v204, v198
	v_mfma_f32_16x16x32_bf16 v[108:111], v[108:111], v[24:27], 0
	v_mfma_f32_16x16x32_bf16 v[100:103], v[100:103], v[24:27], 0
	v_mfma_f32_16x16x32_bf16 v[228:231], v[104:107], v[20:23], v[228:231]
	v_mfma_f32_16x16x32_bf16 v[232:235], v[96:99], v[20:23], v[232:235]
	v_mfma_f32_16x16x32_bf16 v[104:107], v[104:107], v[28:31], v[108:111]
	s_nop 5
	v_fmac_f32_e32 v169, 0x3e38aa3b, v228
	v_fmamk_f32 v228, v198, 0x40a00000, v167
	v_fmac_f32_e32 v177, 0x3e38aa3b, v232
	v_mfma_f32_16x16x32_bf16 v[96:99], v[96:99], v[28:31], v[100:103]
	v_fmac_f32_e32 v207, 0x3e38aa3b, v229
	v_fmac_f32_e32 v228, 0x3e38aa3b, v233
	v_add_f32_e32 v169, v179, v169
	v_mul_f32_e64 v100, -v199, v204
	v_fma_f32 v101, 0, v199, v100
	v_fmac_f32_e32 v101, 0x3e38aa3b, v104
	v_fmamk_f32 v102, v199, 0x40800000, v100
	v_fma_f32 v103, -v199, v204, v199
	v_fmamk_f32 v104, v199, 0x40a00000, v100
	v_add_f32_e32 v177, v181, v177
	v_add_f32_e32 v207, v183, v207
	v_add_f32_e32 v228, v185, v228
	v_fmac_f32_e32 v102, 0x3e38aa3b, v96
	v_fmac_f32_e32 v103, 0x3e38aa3b, v105
	v_fmac_f32_e32 v104, 0x3e38aa3b, v97
	v_max_f32_e32 v206, v169, v177
	v_max_f32_e32 v229, v207, v228
	v_add_f32_e32 v101, v179, v101
	v_add_f32_e32 v96, v181, v102
	v_add_f32_e32 v103, v183, v103
	v_add_f32_e32 v97, v185, v104
	v_max3_f32 v206, v206, s73, v229
	v_fma_f32 v229, 2.0, v198, v167
	v_max_f32_e32 v102, v101, v96
	v_max_f32_e32 v104, v103, v97
	v_fmac_f32_e32 v229, 0x3e38aa3b, v230
	v_fmamk_f32 v230, v198, 0x40c00000, v167
	v_fmamk_f32 v233, v198, 0x40400000, v167
	v_fmac_f32_e32 v167, 0x40e00000, v198
	v_max3_f32 v102, v102, s73, v104
	v_fma_f32 v104, 2.0, v199, v100
	v_fmac_f32_e32 v230, 0x3e38aa3b, v234
	v_fmac_f32_e32 v233, 0x3e38aa3b, v231
	v_fmac_f32_e32 v167, 0x3e38aa3b, v235
	v_fmac_f32_e32 v104, 0x3e38aa3b, v106
	v_fmamk_f32 v105, v199, 0x40c00000, v100
	v_fmamk_f32 v106, v199, 0x40400000, v100
	v_fmac_f32_e32 v100, 0x40e00000, v199
	v_add_f32_e32 v229, v187, v229
	v_add_f32_e32 v230, v189, v230
	v_add_f32_e32 v231, v202, v233
	v_add_f32_e32 v233, v203, v167
	v_fmac_f32_e32 v105, 0x3e38aa3b, v98
	v_fmac_f32_e32 v106, 0x3e38aa3b, v107
	v_fmac_f32_e32 v100, 0x3e38aa3b, v99
	v_max_f32_e32 v232, v229, v230
	v_max_f32_e32 v167, v231, v233
	v_add_f32_e32 v104, v187, v104
	v_add_f32_e32 v98, v189, v105
	v_add_f32_e32 v106, v202, v106
	v_add_f32_e32 v99, v203, v100
	v_max3_f32 v167, v206, v232, v167
	v_max_f32_e32 v105, v104, v98
	v_max_f32_e32 v100, v106, v99
	v_mov_b32_e32 v206, v167
	v_max3_f32 v100, v102, v105, v100
	v_mov_b32_e32 v102, v100
	s_nop 0
	v_permlane16_swap_b32_e32 v206, v167
	s_nop 0
	v_permlane16_swap_b32_e32 v102, v100
	v_max_f32_e32 v167, v167, v206
	v_max_f32_e32 v100, v100, v102
	v_mov_b32_e32 v206, v167
	v_mov_b32_e32 v102, v100
	s_nop 1
	v_permlane32_swap_b32_e32 v206, v167
	v_permlane32_swap_b32_e32 v102, v100
	v_max3_f32 v206, v175, v167, v206
	v_sub_f32_e32 v177, v177, v206
	v_max3_f32 v202, v173, v100, v102
	v_sub_f32_e32 v167, v169, v206
	v_exp_f32_e32 v241, v177
	v_sub_f32_e32 v177, v228, v206
	v_sub_f32_e32 v101, v101, v202
	v_sub_f32_e32 v175, v175, v206
	v_exp_f32_e32 v167, v167
	v_sub_f32_e32 v169, v207, v206
	v_exp_f32_e32 v243, v177
	v_sub_f32_e32 v177, v230, v206
	v_sub_f32_e32 v100, v173, v202
	v_exp_f32_e32 v173, v101
	v_sub_f32_e32 v101, v103, v202
	v_sub_f32_e32 v96, v96, v202
	v_exp_f32_e32 v169, v169
	v_sub_f32_e32 v207, v229, v206
	v_exp_f32_e32 v245, v177
	v_sub_f32_e32 v177, v233, v206
	v_exp_f32_e32 v249, v175
	v_exp_f32_e32 v175, v101
	v_sub_f32_e32 v101, v104, v202
	v_exp_f32_e32 v181, v96
	v_sub_f32_e32 v96, v97, v202
	v_exp_f32_e32 v237, v207
	v_sub_f32_e32 v207, v231, v206
	v_exp_f32_e32 v247, v177
	v_exp_f32_e32 v177, v101
	v_sub_f32_e32 v101, v106, v202
	v_exp_f32_e32 v185, v96
	v_sub_f32_e32 v96, v98, v202
	v_exp_f32_e32 v239, v207
	v_exp_f32_e32 v179, v101
	v_exp_f32_e32 v187, v96
	v_sub_f32_e32 v96, v99, v202
	v_pk_add_f32 v[228:229], v[166:167], 0 op_sel_hi:[1,0]
	v_exp_f32_e32 v189, v96
	v_pk_add_f32 v[96:97], v[172:173], 0 op_sel_hi:[1,0]
	v_pk_add_f32 v[228:229], v[168:169], v[228:229]
	v_pk_add_f32 v[96:97], v[174:175], v[96:97]
	v_pk_add_f32 v[228:229], v[236:237], v[228:229]
	v_pk_add_f32 v[96:97], v[176:177], v[96:97]
	v_pk_add_f32 v[228:229], v[238:239], v[228:229]
	v_exp_f32_e32 v183, v100
	v_pk_add_f32 v[96:97], v[178:179], v[96:97]
	v_pk_add_f32 v[228:229], v[240:241], v[228:229]
	v_pk_add_f32 v[96:97], v[180:181], v[96:97]
	v_pk_add_f32 v[228:229], v[242:243], v[228:229]
	v_pk_add_f32 v[96:97], v[184:185], v[96:97]
	v_pk_add_f32 v[228:229], v[244:245], v[228:229]
	v_pk_add_f32 v[96:97], v[186:187], v[96:97]
	v_pk_add_f32 v[228:229], v[246:247], v[228:229]
	v_mov_b32_e32 v166, v249
	v_pk_add_f32 v[96:97], v[188:189], v[96:97]
	v_mov_b32_e32 v100, v183
	v_pk_fma_f32 v[156:157], v[156:157], v[248:249], v[228:229]
	v_cvt_pk_bf16_f32 v228, v167, v169
	v_cvt_pk_bf16_f32 v229, v237, v239
	v_cvt_pk_bf16_f32 v230, v241, v243
	v_cvt_pk_bf16_f32 v231, v245, v247
	v_pk_mul_f32 v[62:63], v[62:63], v[166:167] op_sel_hi:[1,0]
	v_pk_mul_f32 v[60:61], v[60:61], v[166:167] op_sel_hi:[1,0]
	v_pk_mul_f32 v[58:59], v[58:59], v[166:167] op_sel_hi:[1,0]
	v_pk_mul_f32 v[56:57], v[56:57], v[166:167] op_sel_hi:[1,0]
	v_pk_mul_f32 v[54:55], v[54:55], v[166:167] op_sel_hi:[1,0]
	v_pk_mul_f32 v[52:53], v[52:53], v[166:167] op_sel_hi:[1,0]
	v_pk_mul_f32 v[50:51], v[50:51], v[166:167] op_sel_hi:[1,0]
	v_pk_mul_f32 v[48:49], v[48:49], v[166:167] op_sel_hi:[1,0]
	v_pk_fma_f32 v[154:155], v[154:155], v[182:183], v[96:97]
	v_cvt_pk_bf16_f32 v96, v173, v175
	v_cvt_pk_bf16_f32 v97, v177, v179
	v_cvt_pk_bf16_f32 v98, v181, v185
	v_cvt_pk_bf16_f32 v99, v187, v189
	v_pk_mul_f32 v[46:47], v[46:47], v[100:101] op_sel_hi:[1,0]
	v_pk_mul_f32 v[44:45], v[44:45], v[100:101] op_sel_hi:[1,0]
	v_pk_mul_f32 v[42:43], v[42:43], v[100:101] op_sel_hi:[1,0]
	v_pk_mul_f32 v[40:41], v[40:41], v[100:101] op_sel_hi:[1,0]
	v_pk_mul_f32 v[38:39], v[38:39], v[100:101] op_sel_hi:[1,0]
	v_pk_mul_f32 v[36:37], v[36:37], v[100:101] op_sel_hi:[1,0]
	v_pk_mul_f32 v[34:35], v[34:35], v[100:101] op_sel_hi:[1,0]
	v_pk_mul_f32 v[32:33], v[32:33], v[100:101] op_sel_hi:[1,0]
	v_mfma_f32_16x16x32_bf16 v[60:63], v[136:139], v[228:231], v[60:63]
	v_mfma_f32_16x16x32_bf16 v[56:59], v[140:143], v[228:231], v[56:59]
	v_mfma_f32_16x16x32_bf16 v[52:55], v[132:135], v[228:231], v[52:55]
	v_mfma_f32_16x16x32_bf16 v[48:51], v[128:131], v[228:231], v[48:51]
	v_mfma_f32_16x16x32_bf16 v[44:47], v[136:139], v[96:99], v[44:47]
	v_mfma_f32_16x16x32_bf16 v[40:43], v[140:143], v[96:99], v[40:43]
	v_mfma_f32_16x16x32_bf16 v[36:39], v[132:135], v[96:99], v[36:39]
	v_mfma_f32_16x16x32_bf16 v[32:35], v[128:131], v[96:99], v[32:35]
	s_waitcnt vmcnt(0)
	s_and_b64 vcc, exec, s[4:5]
	s_cbranch_vccnz .LBB0_203
	v_mov_b64_e32 v[108:109], v[112:113]
	v_mov_b64_e32 v[104:105], v[116:117]
	v_mov_b64_e32 v[100:101], v[120:121]
	v_mov_b64_e32 v[96:97], v[124:125]
	s_mov_b32 s82, s23
	s_mov_b32 s4, s24
	v_mov_b64_e32 v[110:111], v[114:115]
	v_mov_b64_e32 v[106:107], v[118:119]
	v_mov_b64_e32 v[102:103], v[122:123]
	v_mov_b64_e32 v[98:99], v[126:127]
	v_mov_b32_e32 v172, v201
	v_mov_b32_e32 v177, v205
	v_mov_b32_e32 v175, v206
	v_mov_b32_e32 v173, v202
	s_andn2_b64 vcc, exec, s[12:13]
	s_mov_b64 s[0:1], -1
	s_cbranch_vccz .LBB0_193
	s_branch .LBB0_198
